# GEMM K-loop LDS-DMA loads rewritten to scalar-base plus 32-bit lane offset form where the base is block-local; 36 address VALU ops removed (kept as candidate)
# speedup vs baseline: 1.0155x; 1.0155x over previous
.LBB0_32:
	v_lshl_add_u64 v[8:9], s[4:5], 0, v[208:209]
	v_mov_b32_e32 v129, v209
	v_lshl_add_u64 v[10:11], s[4:5], 0, v[128:129]
	s_add_i32 m0, s21, 0x18000
	v_lshl_add_u64 v[8:9], v[8:9], 0, s[76:77]
	v_lshl_add_u64 v[12:13], s[12:13], 0, v[208:209]
	s_and_b32 s35, s8, 3
	s_lshl_b32 s11, s66, 6
	s_lshl_b32 s10, s66, 13
	s_waitcnt vmcnt(2)
	s_barrier
	global_load_lds_dwordx4 v[8:9], off
	v_lshl_add_u64 v[8:9], v[10:11], 0, s[76:77]
	s_add_i32 m0, s21, 0x1a000
	s_add_i32 s17, s21, 0x8000
	s_add_i32 s40, s21, 0xa000
	v_lshl_add_u64 v[14:15], s[12:13], 0, v[128:129]
	global_load_lds_dwordx4 v[8:9], off
	v_lshl_add_u64 v[8:9], v[12:13], 0, s[76:77]
	s_mov_b32 m0, s17
	s_add_u32 s8, s4, 0x40080
	global_load_lds_dwordx4 v[8:9], off
	v_lshl_add_u64 v[8:9], v[14:15], 0, s[76:77]
	s_mov_b32 m0, s40
	s_addc_u32 s9, s5, 0
	global_load_lds_dwordx4 v[8:9], off
	s_add_i32 m0, s21, 0x1c000
	s_nop 0
	global_load_lds_dwordx4 v208, s[8:9]
	v_lshl_add_u64 v[8:9], s[8:9], 0, v[128:129]
	s_add_i32 m0, s21, 0x1e000
	v_lshlrev_b32_e32 v0, 13, v0
	global_load_lds_dwordx4 v128, s[8:9]
	v_lshlrev_b32_e32 v5, 13, v5
	v_and_b32_e32 v0, 0x7fffc000, v0
	v_lshlrev_b32_e32 v9, 2, v221
	v_and_b32_e32 v5, 0x7fffc000, v5
	v_lshl_add_u32 v0, v1, 10, v0
	v_lshl_or_b32 v8, v221, 6, v223
	v_and_b32_e32 v9, 32, v9
	v_lshl_add_u32 v4, v4, 10, v5
	v_or_b32_e32 v0, v0, v2
	v_bitop3_b32 v8, v8, s10, v9 bitop3:0xde
	s_waitcnt vmcnt(6)
	v_or_b32_e32 v4, v4, v6
	v_add_lshl_u32 v132, v0, v3, 1
	v_mov_b32_e32 v2, v209
	v_mov_b32_e32 v3, v209
	v_readlane_b32 s8, v254, 22
	v_add_lshl_u32 v130, v4, v7, 1
	v_mov_b32_e32 v0, v209
	v_mov_b32_e32 v1, v209
	v_add_u32_e32 v139, 0, v8
	v_mov_b64_e32 v[6:7], v[2:3]
	v_mov_b64_e32 v[18:19], v[2:3]
	v_mov_b64_e32 v[22:23], v[2:3]
	v_mov_b64_e32 v[34:35], v[2:3]
	v_mov_b64_e32 v[38:39], v[2:3]
	v_mov_b64_e32 v[50:51], v[2:3]
	v_mov_b64_e32 v[54:55], v[2:3]
	v_mov_b64_e32 v[10:11], v[2:3]
	v_mov_b64_e32 v[14:15], v[2:3]
	v_mov_b64_e32 v[26:27], v[2:3]
	v_mov_b64_e32 v[30:31], v[2:3]
	v_mov_b64_e32 v[42:43], v[2:3]
	v_mov_b64_e32 v[46:47], v[2:3]
	v_mov_b64_e32 v[58:59], v[2:3]
	v_mov_b64_e32 v[62:63], v[2:3]
	v_mov_b64_e32 v[66:67], v[2:3]
	v_mov_b64_e32 v[70:71], v[2:3]
	v_mov_b64_e32 v[82:83], v[2:3]
	v_mov_b64_e32 v[86:87], v[2:3]
	v_mov_b64_e32 v[114:115], v[2:3]
	v_mov_b64_e32 v[118:119], v[2:3]
	v_mov_b64_e32 v[98:99], v[2:3]
	v_mov_b64_e32 v[102:103], v[2:3]
	v_mov_b64_e32 v[74:75], v[2:3]
	v_mov_b64_e32 v[78:79], v[2:3]
	v_mov_b64_e32 v[90:91], v[2:3]
	v_mov_b64_e32 v[94:95], v[2:3]
	v_mov_b64_e32 v[122:123], v[2:3]
	v_mov_b64_e32 v[126:127], v[2:3]
	v_mov_b64_e32 v[106:107], v[2:3]
	v_mov_b64_e32 v[110:111], v[2:3]
	s_mov_b32 s34, s8
	v_readlane_b32 s8, v254, 27
	s_mov_b32 s81, s11
	v_or_b32_e32 v228, s11, v221
	v_lshl_or_b32 v138, s35, 12, v247
	v_mov_b32_e32 v131, v209
	v_mov_b32_e32 v133, v209
	s_mov_b32 s41, 0
	v_mov_b64_e32 v[4:5], v[0:1]
	v_mov_b64_e32 v[16:17], v[0:1]
	v_mov_b64_e32 v[20:21], v[0:1]
	v_mov_b64_e32 v[32:33], v[0:1]
	v_mov_b64_e32 v[36:37], v[0:1]
	v_mov_b64_e32 v[48:49], v[0:1]
	v_mov_b64_e32 v[52:53], v[0:1]
	v_mov_b64_e32 v[8:9], v[0:1]
	v_mov_b64_e32 v[12:13], v[0:1]
	v_mov_b64_e32 v[24:25], v[0:1]
	v_mov_b64_e32 v[28:29], v[0:1]
	v_mov_b64_e32 v[40:41], v[0:1]
	v_mov_b64_e32 v[44:45], v[0:1]
	v_mov_b64_e32 v[56:57], v[0:1]
	v_mov_b64_e32 v[60:61], v[0:1]
	v_mov_b64_e32 v[64:65], v[0:1]
	v_mov_b64_e32 v[68:69], v[0:1]
	v_mov_b64_e32 v[80:81], v[0:1]
	v_mov_b64_e32 v[84:85], v[0:1]
	v_mov_b64_e32 v[112:113], v[0:1]
	v_mov_b64_e32 v[116:117], v[0:1]
	v_mov_b64_e32 v[96:97], v[0:1]
	v_mov_b64_e32 v[100:101], v[0:1]
	v_mov_b64_e32 v[72:73], v[0:1]
	v_mov_b64_e32 v[76:77], v[0:1]
	v_mov_b64_e32 v[88:89], v[0:1]
	v_mov_b64_e32 v[92:93], v[0:1]
	v_mov_b64_e32 v[120:121], v[0:1]
	v_mov_b64_e32 v[124:125], v[0:1]
	v_mov_b64_e32 v[104:105], v[0:1]
	v_mov_b64_e32 v[108:109], v[0:1]
	s_mov_b32 s89, s8
	s_barrier
	v_readlane_b32 s9, v254, 28

.LBB0_40:
	s_add_u32 s4, s12, vcc_lo
	s_addc_u32 s5, s13, vcc_hi
	s_add_u32 s4, s4, 0x100
	s_addc_u32 s5, s5, 0
	s_add_u32 s15, s64, vcc_lo
	s_addc_u32 s28, s65, vcc_hi
	s_add_i32 s29, 0, 0x10000
	s_cmpk_eq_i32 vcc_lo, 0x700
	s_cselect_b32 s37, s61, s5
	s_cselect_b32 s36, s87, s4
	s_cselect_b32 s5, s59, s28
	s_cselect_b32 s4, s16, s15
	s_add_i32 s15, 0, 0x14000
	v_add_u32_e32 v152, s29, v138
	v_add_u32_e32 v168, s15, v138
	ds_read_b128 v[140:143], v152
	ds_read_b128 v[144:147], v152 offset:1024
	ds_read_b128 v[148:151], v152 offset:2048
	ds_read_b128 v[152:155], v152 offset:3072
	ds_read_b128 v[156:159], v168
	ds_read_b128 v[160:163], v168 offset:1024
	ds_read_b128 v[164:167], v168 offset:2048
	ds_read_b128 v[168:171], v168 offset:3072
	v_lshl_add_u64 v[204:205], v[134:135], 0, vcc
	s_add_i32 m0, s21, 0xc000
	ds_read_b128 v[172:175], v139
	ds_read_b128 v[176:179], v139 offset:1024
	ds_read_b128 v[180:183], v139 offset:2048
	ds_read_b128 v[184:187], v139 offset:3072
	ds_read_b128 v[188:191], v139 offset:4096
	ds_read_b128 v[192:195], v139 offset:5120
	ds_read_b128 v[196:199], v139 offset:6144
	ds_read_b128 v[200:203], v139 offset:7168
	global_load_lds_dwordx4 v[204:205], off
	v_lshl_add_u64 v[204:205], v[136:137], 0, vcc
	s_add_i32 m0, s21, 0xe000
	s_nop 0
	global_load_lds_dwordx4 v[204:205], off
	s_waitcnt vmcnt(8)
	s_waitcnt lgkmcnt(0)
	s_barrier
	s_setprio 1
	s_waitcnt lgkmcnt(0)
	v_mfma_f32_16x16x32_bf16 v[108:111], v[140:143], v[172:175], v[108:111]
	v_mfma_f32_16x16x32_bf16 v[104:107], v[148:151], v[172:175], v[104:107]
	v_mfma_f32_16x16x32_bf16 v[124:127], v[140:143], v[180:183], v[124:127]
	v_mfma_f32_16x16x32_bf16 v[120:123], v[148:151], v[180:183], v[120:123]
	v_mfma_f32_16x16x32_bf16 v[92:95], v[140:143], v[188:191], v[92:95]
	v_mfma_f32_16x16x32_bf16 v[88:91], v[148:151], v[188:191], v[88:91]
	v_mfma_f32_16x16x32_bf16 v[76:79], v[140:143], v[196:199], v[76:79]
	v_mfma_f32_16x16x32_bf16 v[72:75], v[148:151], v[196:199], v[72:75]
	v_mfma_f32_16x16x32_bf16 v[108:111], v[144:147], v[176:179], v[108:111]
	v_mfma_f32_16x16x32_bf16 v[104:107], v[152:155], v[176:179], v[104:107]
	v_mfma_f32_16x16x32_bf16 v[124:127], v[144:147], v[184:187], v[124:127]
	v_mfma_f32_16x16x32_bf16 v[120:123], v[152:155], v[184:187], v[120:123]
	v_mfma_f32_16x16x32_bf16 v[92:95], v[144:147], v[192:195], v[92:95]
	v_mfma_f32_16x16x32_bf16 v[88:91], v[152:155], v[192:195], v[88:91]
	v_mfma_f32_16x16x32_bf16 v[76:79], v[144:147], v[200:203], v[76:79]
	v_mfma_f32_16x16x32_bf16 v[72:75], v[152:155], v[200:203], v[72:75]
	s_setprio 0
	s_setprio 1
	v_mfma_f32_16x16x32_bf16 v[100:103], v[156:159], v[172:175], v[100:103]
	v_mfma_f32_16x16x32_bf16 v[96:99], v[164:167], v[172:175], v[96:99]
	v_mfma_f32_16x16x32_bf16 v[116:119], v[156:159], v[180:183], v[116:119]
	v_mfma_f32_16x16x32_bf16 v[112:115], v[164:167], v[180:183], v[112:115]
	v_mfma_f32_16x16x32_bf16 v[84:87], v[156:159], v[188:191], v[84:87]
	v_mfma_f32_16x16x32_bf16 v[80:83], v[164:167], v[188:191], v[80:83]
	v_mfma_f32_16x16x32_bf16 v[68:71], v[156:159], v[196:199], v[68:71]
	v_mfma_f32_16x16x32_bf16 v[64:67], v[164:167], v[196:199], v[64:67]
	v_mfma_f32_16x16x32_bf16 v[100:103], v[160:163], v[176:179], v[100:103]
	v_mfma_f32_16x16x32_bf16 v[96:99], v[168:171], v[176:179], v[96:99]
	v_mfma_f32_16x16x32_bf16 v[116:119], v[160:163], v[184:187], v[116:119]
	v_mfma_f32_16x16x32_bf16 v[112:115], v[168:171], v[184:187], v[112:115]
	v_mfma_f32_16x16x32_bf16 v[84:87], v[160:163], v[192:195], v[84:87]
	v_mfma_f32_16x16x32_bf16 v[80:83], v[168:171], v[192:195], v[80:83]
	v_mfma_f32_16x16x32_bf16 v[68:71], v[160:163], v[200:203], v[68:71]
	v_mfma_f32_16x16x32_bf16 v[64:67], v[168:171], v[200:203], v[64:67]
	s_setprio 0
	s_barrier
	s_add_i32 s28, s29, s49
	v_lshl_add_u64 v[204:205], s[4:5], 0, v[208:209]
	s_mov_b32 m0, s28
	ds_read_b128 v[172:175], v139 offset:16384
	ds_read_b128 v[176:179], v139 offset:17408
	ds_read_b128 v[180:183], v139 offset:18432
	ds_read_b128 v[184:187], v139 offset:19456
	ds_read_b128 v[188:191], v139 offset:20480
	ds_read_b128 v[192:195], v139 offset:21504
	ds_read_b128 v[196:199], v139 offset:22528
	ds_read_b128 v[200:203], v139 offset:23552
	global_load_lds_dwordx4 v208, s[4:5]
	s_add_i32 m0, s28, 0x2000
	s_add_u32 s28, s4, 0x40000
	v_lshl_add_u64 v[206:207], s[4:5], 0, v[128:129]
	s_addc_u32 s29, s5, 0
	s_add_i32 s15, s15, s49
	global_load_lds_dwordx4 v128, s[4:5]
	s_mov_b32 m0, s15
	v_lshl_add_u64 v[212:213], s[36:37], 0, v[128:129]
	global_load_lds_dwordx4 v208, s[28:29]
	s_add_i32 m0, s15, 0x2000
	s_nop 0
	global_load_lds_dwordx4 v128, s[28:29]
	v_lshl_add_u64 v[210:211], s[36:37], 0, v[208:209]
	s_mov_b32 m0, s21
	s_nop 0
	global_load_lds_dwordx4 v208, s[36:37]
	s_mov_b32 m0, s33
	s_nop 0
	global_load_lds_dwordx4 v128, s[36:37]
	s_waitcnt vmcnt(8)
	s_waitcnt lgkmcnt(0)
	s_barrier
	s_setprio 1
	s_waitcnt lgkmcnt(0)
	v_mfma_f32_16x16x32_bf16 v[60:63], v[140:143], v[172:175], v[60:63]
	v_mfma_f32_16x16x32_bf16 v[56:59], v[148:151], v[172:175], v[56:59]
	v_mfma_f32_16x16x32_bf16 v[44:47], v[140:143], v[180:183], v[44:47]
	v_mfma_f32_16x16x32_bf16 v[40:43], v[148:151], v[180:183], v[40:43]
	v_mfma_f32_16x16x32_bf16 v[28:31], v[140:143], v[188:191], v[28:31]
	v_mfma_f32_16x16x32_bf16 v[24:27], v[148:151], v[188:191], v[24:27]
	v_mfma_f32_16x16x32_bf16 v[12:15], v[140:143], v[196:199], v[12:15]
	v_mfma_f32_16x16x32_bf16 v[8:11], v[148:151], v[196:199], v[8:11]
	v_mfma_f32_16x16x32_bf16 v[60:63], v[144:147], v[176:179], v[60:63]
	v_mfma_f32_16x16x32_bf16 v[56:59], v[152:155], v[176:179], v[56:59]
	v_mfma_f32_16x16x32_bf16 v[44:47], v[144:147], v[184:187], v[44:47]
	v_mfma_f32_16x16x32_bf16 v[40:43], v[152:155], v[184:187], v[40:43]
	v_mfma_f32_16x16x32_bf16 v[28:31], v[144:147], v[192:195], v[28:31]
	v_mfma_f32_16x16x32_bf16 v[24:27], v[152:155], v[192:195], v[24:27]
	v_mfma_f32_16x16x32_bf16 v[12:15], v[144:147], v[200:203], v[12:15]
	v_mfma_f32_16x16x32_bf16 v[8:11], v[152:155], v[200:203], v[8:11]
	s_setprio 0
	s_setprio 1
	v_mfma_f32_16x16x32_bf16 v[52:55], v[156:159], v[172:175], v[52:55]
	v_mfma_f32_16x16x32_bf16 v[48:51], v[164:167], v[172:175], v[48:51]
	v_mfma_f32_16x16x32_bf16 v[36:39], v[156:159], v[180:183], v[36:39]
	v_mfma_f32_16x16x32_bf16 v[32:35], v[164:167], v[180:183], v[32:35]
	v_mfma_f32_16x16x32_bf16 v[20:23], v[156:159], v[188:191], v[20:23]
	v_mfma_f32_16x16x32_bf16 v[16:19], v[164:167], v[188:191], v[16:19]
	v_mfma_f32_16x16x32_bf16 v[4:7], v[156:159], v[196:199], v[4:7]
	v_mfma_f32_16x16x32_bf16 v[0:3], v[164:167], v[196:199], v[0:3]
	v_mfma_f32_16x16x32_bf16 v[52:55], v[160:163], v[176:179], v[52:55]
	v_mfma_f32_16x16x32_bf16 v[48:51], v[168:171], v[176:179], v[48:51]
	v_mfma_f32_16x16x32_bf16 v[36:39], v[160:163], v[184:187], v[36:39]
	v_mfma_f32_16x16x32_bf16 v[32:35], v[168:171], v[184:187], v[32:35]
	v_mfma_f32_16x16x32_bf16 v[20:23], v[160:163], v[192:195], v[20:23]
	v_mfma_f32_16x16x32_bf16 v[16:19], v[168:171], v[192:195], v[16:19]
	v_mfma_f32_16x16x32_bf16 v[4:7], v[160:163], v[200:203], v[4:7]
	v_mfma_f32_16x16x32_bf16 v[0:3], v[168:171], v[200:203], v[0:3]
	s_setprio 0
	s_barrier
	s_add_i32 s15, 0, 0x18000
	s_add_i32 s80, 0, 0x1c000
	v_add_u32_e32 v152, s15, v138
	v_add_u32_e32 v168, s80, v138
	ds_read_b128 v[140:143], v152
	ds_read_b128 v[144:147], v152 offset:1024
	ds_read_b128 v[148:151], v152 offset:2048
	ds_read_b128 v[152:155], v152 offset:3072
	ds_read_b128 v[156:159], v168
	ds_read_b128 v[160:163], v168 offset:1024
	ds_read_b128 v[164:167], v168 offset:2048
	ds_read_b128 v[168:171], v168 offset:3072
	s_add_u32 s28, s36, 0x40000
	s_addc_u32 s29, s37, 0
	s_mov_b32 m0, s68
	ds_read_b128 v[172:175], v139 offset:32768
	ds_read_b128 v[176:179], v139 offset:33792
	ds_read_b128 v[180:183], v139 offset:34816
	ds_read_b128 v[184:187], v139 offset:35840
	ds_read_b128 v[188:191], v139 offset:36864
	ds_read_b128 v[192:195], v139 offset:37888
	ds_read_b128 v[196:199], v139 offset:38912
	ds_read_b128 v[200:203], v139 offset:39936
	global_load_lds_dwordx4 v208, s[28:29]
	v_lshl_add_u64 v[224:225], s[28:29], 0, v[128:129]
	s_mov_b32 m0, s69
	s_nop 0
	global_load_lds_dwordx4 v128, s[28:29]
	s_waitcnt vmcnt(8)
	s_waitcnt lgkmcnt(0)
	s_barrier
	s_setprio 1
	s_waitcnt lgkmcnt(0)
	v_mfma_f32_16x16x32_bf16 v[108:111], v[140:143], v[172:175], v[108:111]
	v_mfma_f32_16x16x32_bf16 v[104:107], v[148:151], v[172:175], v[104:107]
	v_mfma_f32_16x16x32_bf16 v[124:127], v[140:143], v[180:183], v[124:127]
	v_mfma_f32_16x16x32_bf16 v[120:123], v[148:151], v[180:183], v[120:123]
	v_mfma_f32_16x16x32_bf16 v[92:95], v[140:143], v[188:191], v[92:95]
	v_mfma_f32_16x16x32_bf16 v[88:91], v[148:151], v[188:191], v[88:91]
	v_mfma_f32_16x16x32_bf16 v[76:79], v[140:143], v[196:199], v[76:79]
	v_mfma_f32_16x16x32_bf16 v[72:75], v[148:151], v[196:199], v[72:75]
	v_mfma_f32_16x16x32_bf16 v[108:111], v[144:147], v[176:179], v[108:111]
	v_mfma_f32_16x16x32_bf16 v[104:107], v[152:155], v[176:179], v[104:107]
	v_mfma_f32_16x16x32_bf16 v[124:127], v[144:147], v[184:187], v[124:127]
	v_mfma_f32_16x16x32_bf16 v[120:123], v[152:155], v[184:187], v[120:123]
	v_mfma_f32_16x16x32_bf16 v[92:95], v[144:147], v[192:195], v[92:95]
	v_mfma_f32_16x16x32_bf16 v[88:91], v[152:155], v[192:195], v[88:91]
	v_mfma_f32_16x16x32_bf16 v[76:79], v[144:147], v[200:203], v[76:79]
	v_mfma_f32_16x16x32_bf16 v[72:75], v[152:155], v[200:203], v[72:75]
	s_setprio 0
	s_setprio 1
	v_mfma_f32_16x16x32_bf16 v[100:103], v[156:159], v[172:175], v[100:103]
	v_mfma_f32_16x16x32_bf16 v[96:99], v[164:167], v[172:175], v[96:99]
	v_mfma_f32_16x16x32_bf16 v[116:119], v[156:159], v[180:183], v[116:119]
	v_mfma_f32_16x16x32_bf16 v[112:115], v[164:167], v[180:183], v[112:115]
	v_mfma_f32_16x16x32_bf16 v[84:87], v[156:159], v[188:191], v[84:87]
	v_mfma_f32_16x16x32_bf16 v[80:83], v[164:167], v[188:191], v[80:83]
	v_mfma_f32_16x16x32_bf16 v[68:71], v[156:159], v[196:199], v[68:71]
	v_mfma_f32_16x16x32_bf16 v[64:67], v[164:167], v[196:199], v[64:67]
	v_mfma_f32_16x16x32_bf16 v[100:103], v[160:163], v[176:179], v[100:103]
	v_mfma_f32_16x16x32_bf16 v[96:99], v[168:171], v[176:179], v[96:99]
	v_mfma_f32_16x16x32_bf16 v[116:119], v[160:163], v[184:187], v[116:119]
	v_mfma_f32_16x16x32_bf16 v[112:115], v[168:171], v[184:187], v[112:115]
	v_mfma_f32_16x16x32_bf16 v[84:87], v[160:163], v[192:195], v[84:87]
	v_mfma_f32_16x16x32_bf16 v[80:83], v[168:171], v[192:195], v[80:83]
	v_mfma_f32_16x16x32_bf16 v[68:71], v[160:163], v[200:203], v[68:71]
	v_mfma_f32_16x16x32_bf16 v[64:67], v[168:171], v[200:203], v[64:67]
	s_setprio 0
	s_barrier
	s_add_i32 s15, s15, s49
	v_lshl_add_u64 v[204:205], v[204:205], 0, s[76:77]
	s_mov_b32 m0, s15
	ds_read_b128 v[172:175], v139 offset:49152
	ds_read_b128 v[176:179], v139 offset:50176
	ds_read_b128 v[180:183], v139 offset:51200
	ds_read_b128 v[184:187], v139 offset:52224
	ds_read_b128 v[188:191], v139 offset:53248
	ds_read_b128 v[192:195], v139 offset:54272
	ds_read_b128 v[196:199], v139 offset:55296
	ds_read_b128 v[200:203], v139 offset:56320
	global_load_lds_dwordx4 v[204:205], off
	s_add_i32 m0, s15, 0x2000
	s_add_u32 s4, s4, 0x40080
	v_lshl_add_u64 v[204:205], v[206:207], 0, s[76:77]
	s_addc_u32 s5, s5, 0
	s_add_i32 s15, s80, s49
	global_load_lds_dwordx4 v[204:205], off
	s_mov_b32 m0, s15
	s_nop 0
	global_load_lds_dwordx4 v208, s[4:5]
	s_add_i32 m0, s15, 0x2000
	s_nop 0
	global_load_lds_dwordx4 v128, s[4:5]
	v_lshl_add_u64 v[204:205], v[210:211], 0, s[76:77]
	s_mov_b32 m0, s17
	s_nop 0
	global_load_lds_dwordx4 v[204:205], off
	v_lshl_add_u64 v[204:205], v[212:213], 0, s[76:77]
	s_mov_b32 m0, s40
	s_nop 0
	global_load_lds_dwordx4 v[204:205], off
	s_waitcnt vmcnt(8)
	s_waitcnt lgkmcnt(0)
	s_barrier
	s_setprio 1
	s_waitcnt lgkmcnt(0)
	v_mfma_f32_16x16x32_bf16 v[60:63], v[140:143], v[172:175], v[60:63]
	v_mfma_f32_16x16x32_bf16 v[56:59], v[148:151], v[172:175], v[56:59]
	v_mfma_f32_16x16x32_bf16 v[44:47], v[140:143], v[180:183], v[44:47]
	v_mfma_f32_16x16x32_bf16 v[40:43], v[148:151], v[180:183], v[40:43]
	v_mfma_f32_16x16x32_bf16 v[28:31], v[140:143], v[188:191], v[28:31]
	v_mfma_f32_16x16x32_bf16 v[24:27], v[148:151], v[188:191], v[24:27]
	v_mfma_f32_16x16x32_bf16 v[12:15], v[140:143], v[196:199], v[12:15]
	v_mfma_f32_16x16x32_bf16 v[8:11], v[148:151], v[196:199], v[8:11]
	v_mfma_f32_16x16x32_bf16 v[60:63], v[144:147], v[176:179], v[60:63]
	v_mfma_f32_16x16x32_bf16 v[56:59], v[152:155], v[176:179], v[56:59]
	v_mfma_f32_16x16x32_bf16 v[44:47], v[144:147], v[184:187], v[44:47]
	v_mfma_f32_16x16x32_bf16 v[40:43], v[152:155], v[184:187], v[40:43]
	v_mfma_f32_16x16x32_bf16 v[28:31], v[144:147], v[192:195], v[28:31]
	v_mfma_f32_16x16x32_bf16 v[24:27], v[152:155], v[192:195], v[24:27]
	v_mfma_f32_16x16x32_bf16 v[12:15], v[144:147], v[200:203], v[12:15]
	v_mfma_f32_16x16x32_bf16 v[8:11], v[152:155], v[200:203], v[8:11]
	s_setprio 0
	s_setprio 1
	v_mfma_f32_16x16x32_bf16 v[52:55], v[156:159], v[172:175], v[52:55]
	v_mfma_f32_16x16x32_bf16 v[48:51], v[164:167], v[172:175], v[48:51]
	v_mfma_f32_16x16x32_bf16 v[36:39], v[156:159], v[180:183], v[36:39]
	v_mfma_f32_16x16x32_bf16 v[32:35], v[164:167], v[180:183], v[32:35]
	v_mfma_f32_16x16x32_bf16 v[20:23], v[156:159], v[188:191], v[20:23]
	v_mfma_f32_16x16x32_bf16 v[16:19], v[164:167], v[188:191], v[16:19]
	v_mfma_f32_16x16x32_bf16 v[4:7], v[156:159], v[196:199], v[4:7]
	v_mfma_f32_16x16x32_bf16 v[0:3], v[164:167], v[196:199], v[0:3]
	v_mfma_f32_16x16x32_bf16 v[52:55], v[160:163], v[176:179], v[52:55]
	v_mfma_f32_16x16x32_bf16 v[48:51], v[168:171], v[176:179], v[48:51]
	v_mfma_f32_16x16x32_bf16 v[36:39], v[160:163], v[184:187], v[36:39]
	v_mfma_f32_16x16x32_bf16 v[32:35], v[168:171], v[184:187], v[32:35]
	v_mfma_f32_16x16x32_bf16 v[20:23], v[160:163], v[192:195], v[20:23]
	v_mfma_f32_16x16x32_bf16 v[16:19], v[168:171], v[192:195], v[16:19]
	v_mfma_f32_16x16x32_bf16 v[4:7], v[160:163], v[200:203], v[4:7]
	v_mfma_f32_16x16x32_bf16 v[0:3], v[168:171], v[200:203], v[0:3]
	s_setprio 0
	s_barrier
	s_add_i32 s14, s14, 2
	s_add_u32 vcc_lo, vcc_lo, 0x100
	s_addc_u32 vcc_hi, vcc_hi, 0
	s_cmp_gt_u32 s14, 13
	s_cbranch_scc0 .LBB0_40
	s_add_u32 s4, s64, 0xffffff00
	s_addc_u32 s5, s65, -1
	s_andn2_b64 vcc, exec, s[10:11]
	s_cbranch_vccnz .LBB0_43
	v_mov_b32_e32 v0, 0
	s_mov_b32 s34, s58
	s_mov_b32 s89, s60
	s_mov_b64 s[12:13], s[18:19]
	s_mov_b32 s41, s86
	v_mov_b32_e32 v1, v0
	v_mov_b32_e32 v2, v0
	v_mov_b32_e32 v3, v0
	v_mov_b32_e32 v4, v0
	v_mov_b32_e32 v5, v0
	v_mov_b32_e32 v6, v0
	v_mov_b32_e32 v7, v0
	v_mov_b32_e32 v16, v0
	v_mov_b32_e32 v17, v0
	v_mov_b32_e32 v18, v0
	v_mov_b32_e32 v19, v0
	v_mov_b32_e32 v20, v0
	v_mov_b32_e32 v21, v0
	v_mov_b32_e32 v22, v0
	v_mov_b32_e32 v23, v0
	v_mov_b32_e32 v32, v0
	v_mov_b32_e32 v33, v0
	v_mov_b32_e32 v34, v0
	v_mov_b32_e32 v35, v0
	v_mov_b32_e32 v36, v0
	v_mov_b32_e32 v37, v0
	v_mov_b32_e32 v38, v0
	v_mov_b32_e32 v39, v0
	v_mov_b32_e32 v48, v0
	v_mov_b32_e32 v49, v0
	v_mov_b32_e32 v50, v0
	v_mov_b32_e32 v51, v0
	v_mov_b32_e32 v52, v0
	v_mov_b32_e32 v53, v0
	v_mov_b32_e32 v54, v0
	v_mov_b32_e32 v55, v0
	v_mov_b32_e32 v8, v0
	v_mov_b32_e32 v9, v0
	v_mov_b32_e32 v10, v0
	v_mov_b32_e32 v11, v0
	v_mov_b32_e32 v12, v0
	v_mov_b32_e32 v13, v0
	v_mov_b32_e32 v14, v0
	v_mov_b32_e32 v15, v0
	v_mov_b32_e32 v24, v0
	v_mov_b32_e32 v25, v0
	v_mov_b32_e32 v26, v0
	v_mov_b32_e32 v27, v0
	v_mov_b32_e32 v28, v0
	v_mov_b32_e32 v29, v0
	v_mov_b32_e32 v30, v0
	v_mov_b32_e32 v31, v0
	v_mov_b32_e32 v40, v0
	v_mov_b32_e32 v41, v0
	v_mov_b32_e32 v42, v0
	v_mov_b32_e32 v43, v0
	v_mov_b32_e32 v44, v0
	v_mov_b32_e32 v45, v0
	v_mov_b32_e32 v46, v0
	v_mov_b32_e32 v47, v0
	v_mov_b32_e32 v56, v0
	v_mov_b32_e32 v57, v0
	v_mov_b32_e32 v58, v0
	v_mov_b32_e32 v59, v0
	v_mov_b32_e32 v60, v0
	v_mov_b32_e32 v61, v0
	v_mov_b32_e32 v62, v0
	v_mov_b32_e32 v63, v0
	v_mov_b32_e32 v64, v0
	v_mov_b32_e32 v65, v0
	v_mov_b32_e32 v66, v0
	v_mov_b32_e32 v67, v0
	v_mov_b32_e32 v68, v0
	v_mov_b32_e32 v69, v0
	v_mov_b32_e32 v70, v0
	v_mov_b32_e32 v71, v0
	v_mov_b32_e32 v80, v0
	v_mov_b32_e32 v81, v0
	v_mov_b32_e32 v82, v0
	v_mov_b32_e32 v83, v0
	v_mov_b32_e32 v84, v0
	v_mov_b32_e32 v85, v0
	v_mov_b32_e32 v86, v0
	v_mov_b32_e32 v87, v0
	v_mov_b32_e32 v112, v0
	v_mov_b32_e32 v113, v0
	v_mov_b32_e32 v114, v0
	v_mov_b32_e32 v115, v0
	v_mov_b32_e32 v116, v0
	v_mov_b32_e32 v117, v0
	v_mov_b32_e32 v118, v0
	v_mov_b32_e32 v119, v0
	v_mov_b32_e32 v96, v0
	v_mov_b32_e32 v97, v0
	v_mov_b32_e32 v98, v0
	v_mov_b32_e32 v99, v0
	v_mov_b32_e32 v100, v0
	v_mov_b32_e32 v101, v0
	v_mov_b32_e32 v102, v0
	v_mov_b32_e32 v103, v0
	v_mov_b32_e32 v72, v0
	v_mov_b32_e32 v73, v0
	v_mov_b32_e32 v74, v0
	v_mov_b32_e32 v75, v0
	v_mov_b32_e32 v76, v0
	v_mov_b32_e32 v77, v0
	v_mov_b32_e32 v78, v0
	v_mov_b32_e32 v79, v0
	v_mov_b32_e32 v88, v0
	v_mov_b32_e32 v89, v0
	v_mov_b32_e32 v90, v0
	v_mov_b32_e32 v91, v0
	v_mov_b32_e32 v92, v0
	v_mov_b32_e32 v93, v0
	v_mov_b32_e32 v94, v0
	v_mov_b32_e32 v95, v0
	v_mov_b32_e32 v120, v0
	v_mov_b32_e32 v121, v0
	v_mov_b32_e32 v122, v0
	v_mov_b32_e32 v123, v0
	v_mov_b32_e32 v124, v0
	v_mov_b32_e32 v125, v0
	v_mov_b32_e32 v126, v0
	v_mov_b32_e32 v127, v0
	v_mov_b32_e32 v104, v0
	v_mov_b32_e32 v105, v0
	v_mov_b32_e32 v106, v0
	v_mov_b32_e32 v107, v0
	v_mov_b32_e32 v108, v0
	v_mov_b32_e32 v109, v0
	v_mov_b32_e32 v110, v0
	v_mov_b32_e32 v111, v0
	s_andn2_b64 vcc, exec, s[8:9]
	s_cbranch_vccnz .LBB0_44
	s_branch .LBB0_45

.LBB0_120:
	v_lshl_add_u64 v[8:9], s[62:63], 0, v[208:209]
	v_mov_b32_e32 v129, v209
	v_lshl_add_u64 v[10:11], s[62:63], 0, v[128:129]
	s_add_i32 m0, s21, 0x18000
	v_lshl_add_u64 v[8:9], v[8:9], 0, s[76:77]
	v_lshl_add_u64 v[12:13], s[12:13], 0, v[208:209]
	s_and_b32 s35, s4, 3
	s_lshl_b32 s9, s66, 6
	s_lshl_b32 s8, s66, 13
	s_waitcnt vmcnt(2)
	s_barrier
	global_load_lds_dwordx4 v[8:9], off
	v_lshl_add_u64 v[8:9], v[10:11], 0, s[76:77]
	s_add_i32 m0, s21, 0x1a000
	s_add_i32 s17, s21, 0x8000
	s_add_i32 s40, s21, 0xa000
	v_lshl_add_u64 v[14:15], s[12:13], 0, v[128:129]
	global_load_lds_dwordx4 v[8:9], off
	v_lshl_add_u64 v[8:9], v[12:13], 0, s[76:77]
	s_mov_b32 m0, s17
	s_add_u32 s4, s62, 0x100080
	global_load_lds_dwordx4 v[8:9], off
	v_lshl_add_u64 v[8:9], v[14:15], 0, s[76:77]
	s_mov_b32 m0, s40
	s_addc_u32 s5, s63, 0
	global_load_lds_dwordx4 v[8:9], off
	s_add_i32 m0, s21, 0x1c000
	s_nop 0
	global_load_lds_dwordx4 v208, s[4:5]
	v_lshl_add_u64 v[8:9], s[4:5], 0, v[128:129]
	s_add_i32 m0, s21, 0x1e000
	v_lshlrev_b32_e32 v0, 15, v0
	global_load_lds_dwordx4 v128, s[4:5]
	v_lshlrev_b32_e32 v5, 15, v5
	v_and_b32_e32 v0, 0x7fff0000, v0
	v_lshlrev_b32_e32 v9, 2, v221
	v_and_b32_e32 v5, 0x7fff0000, v5
	v_lshl_add_u32 v0, v1, 12, v0
	v_lshl_or_b32 v8, v221, 6, v223
	v_and_b32_e32 v9, 32, v9
	v_lshl_add_u32 v4, v4, 12, v5
	v_or_b32_e32 v0, v0, v2
	v_bitop3_b32 v8, v8, s8, v9 bitop3:0xde
	s_waitcnt vmcnt(6)
	v_or_b32_e32 v4, v4, v6
	v_add_lshl_u32 v132, v0, v3, 1
	v_mov_b32_e32 v2, v209
	v_mov_b32_e32 v3, v209
	v_readlane_b32 s4, v254, 22
	v_add_lshl_u32 v130, v4, v7, 1
	v_mov_b32_e32 v0, v209
	v_mov_b32_e32 v1, v209
	v_add_u32_e32 v139, 0, v8
	v_mov_b64_e32 v[6:7], v[2:3]
	v_mov_b64_e32 v[18:19], v[2:3]
	v_mov_b64_e32 v[22:23], v[2:3]
	v_mov_b64_e32 v[34:35], v[2:3]
	v_mov_b64_e32 v[38:39], v[2:3]
	v_mov_b64_e32 v[50:51], v[2:3]
	v_mov_b64_e32 v[54:55], v[2:3]
	v_mov_b64_e32 v[10:11], v[2:3]
	v_mov_b64_e32 v[14:15], v[2:3]
	v_mov_b64_e32 v[26:27], v[2:3]
	v_mov_b64_e32 v[30:31], v[2:3]
	v_mov_b64_e32 v[42:43], v[2:3]
	v_mov_b64_e32 v[46:47], v[2:3]
	v_mov_b64_e32 v[58:59], v[2:3]
	v_mov_b64_e32 v[62:63], v[2:3]
	v_mov_b64_e32 v[66:67], v[2:3]
	v_mov_b64_e32 v[70:71], v[2:3]
	v_mov_b64_e32 v[82:83], v[2:3]
	v_mov_b64_e32 v[86:87], v[2:3]
	v_mov_b64_e32 v[114:115], v[2:3]
	v_mov_b64_e32 v[118:119], v[2:3]
	v_mov_b64_e32 v[98:99], v[2:3]
	v_mov_b64_e32 v[102:103], v[2:3]
	v_mov_b64_e32 v[74:75], v[2:3]
	v_mov_b64_e32 v[78:79], v[2:3]
	v_mov_b64_e32 v[90:91], v[2:3]
	v_mov_b64_e32 v[94:95], v[2:3]
	v_mov_b64_e32 v[122:123], v[2:3]
	v_mov_b64_e32 v[126:127], v[2:3]
	v_mov_b64_e32 v[106:107], v[2:3]
	v_mov_b64_e32 v[110:111], v[2:3]
	s_mov_b32 s34, s4
	v_readlane_b32 s4, v254, 27
	s_mov_b32 s81, s9
	v_or_b32_e32 v228, s9, v221
	v_lshl_or_b32 v138, s35, 12, v247
	v_mov_b32_e32 v131, v209
	v_mov_b32_e32 v133, v209
	s_mov_b32 s41, 0
	v_mov_b64_e32 v[4:5], v[0:1]
	v_mov_b64_e32 v[16:17], v[0:1]
	v_mov_b64_e32 v[20:21], v[0:1]
	v_mov_b64_e32 v[32:33], v[0:1]
	v_mov_b64_e32 v[36:37], v[0:1]
	v_mov_b64_e32 v[48:49], v[0:1]
	v_mov_b64_e32 v[52:53], v[0:1]
	v_mov_b64_e32 v[8:9], v[0:1]
	v_mov_b64_e32 v[12:13], v[0:1]
	v_mov_b64_e32 v[24:25], v[0:1]
	v_mov_b64_e32 v[28:29], v[0:1]
	v_mov_b64_e32 v[40:41], v[0:1]
	v_mov_b64_e32 v[44:45], v[0:1]
	v_mov_b64_e32 v[56:57], v[0:1]
	v_mov_b64_e32 v[60:61], v[0:1]
	v_mov_b64_e32 v[64:65], v[0:1]
	v_mov_b64_e32 v[68:69], v[0:1]
	v_mov_b64_e32 v[80:81], v[0:1]
	v_mov_b64_e32 v[84:85], v[0:1]
	v_mov_b64_e32 v[112:113], v[0:1]
	v_mov_b64_e32 v[116:117], v[0:1]
	v_mov_b64_e32 v[96:97], v[0:1]
	v_mov_b64_e32 v[100:101], v[0:1]
	v_mov_b64_e32 v[72:73], v[0:1]
	v_mov_b64_e32 v[76:77], v[0:1]
	v_mov_b64_e32 v[88:89], v[0:1]
	v_mov_b64_e32 v[92:93], v[0:1]
	v_mov_b64_e32 v[120:121], v[0:1]
	v_mov_b64_e32 v[124:125], v[0:1]
	v_mov_b64_e32 v[104:105], v[0:1]
	v_mov_b64_e32 v[108:109], v[0:1]
	s_mov_b32 s89, s4
	s_barrier
	v_readlane_b32 s5, v254, 28

.LBB0_128:
	s_add_u32 s15, s12, vcc_lo
	s_addc_u32 s28, s13, vcc_hi
	s_add_u32 s15, s15, 0x100
	s_addc_u32 s28, s28, 0
	s_add_u32 s29, s87, vcc_lo
	s_addc_u32 s62, s64, vcc_hi
	s_add_i32 s80, 0, 0x10000
	s_cmpk_eq_i32 vcc_lo, 0x1f00
	s_cselect_b32 s37, s61, s28
	s_cselect_b32 s36, s65, s15
	s_cselect_b32 s63, s59, s62
	s_cselect_b32 s62, s16, s29
	s_add_i32 s15, 0, 0x14000
	v_add_u32_e32 v152, s80, v138
	v_add_u32_e32 v168, s15, v138
	ds_read_b128 v[140:143], v152
	ds_read_b128 v[144:147], v152 offset:1024
	ds_read_b128 v[148:151], v152 offset:2048
	ds_read_b128 v[152:155], v152 offset:3072
	ds_read_b128 v[156:159], v168
	ds_read_b128 v[160:163], v168 offset:1024
	ds_read_b128 v[164:167], v168 offset:2048
	ds_read_b128 v[168:171], v168 offset:3072
	v_lshl_add_u64 v[204:205], v[134:135], 0, vcc
	s_add_i32 m0, s21, 0xc000
	ds_read_b128 v[172:175], v139
	ds_read_b128 v[176:179], v139 offset:1024
	ds_read_b128 v[180:183], v139 offset:2048
	ds_read_b128 v[184:187], v139 offset:3072
	ds_read_b128 v[188:191], v139 offset:4096
	ds_read_b128 v[192:195], v139 offset:5120
	ds_read_b128 v[196:199], v139 offset:6144
	ds_read_b128 v[200:203], v139 offset:7168
	global_load_lds_dwordx4 v[204:205], off
	v_lshl_add_u64 v[204:205], v[136:137], 0, vcc
	s_add_i32 m0, s21, 0xe000
	s_nop 0
	global_load_lds_dwordx4 v[204:205], off
	s_waitcnt vmcnt(8)
	s_waitcnt lgkmcnt(0)
	s_barrier
	s_setprio 1
	s_waitcnt lgkmcnt(0)
	v_mfma_f32_16x16x32_bf16 v[108:111], v[140:143], v[172:175], v[108:111]
	v_mfma_f32_16x16x32_bf16 v[104:107], v[148:151], v[172:175], v[104:107]
	v_mfma_f32_16x16x32_bf16 v[124:127], v[140:143], v[180:183], v[124:127]
	v_mfma_f32_16x16x32_bf16 v[120:123], v[148:151], v[180:183], v[120:123]
	v_mfma_f32_16x16x32_bf16 v[92:95], v[140:143], v[188:191], v[92:95]
	v_mfma_f32_16x16x32_bf16 v[88:91], v[148:151], v[188:191], v[88:91]
	v_mfma_f32_16x16x32_bf16 v[76:79], v[140:143], v[196:199], v[76:79]
	v_mfma_f32_16x16x32_bf16 v[72:75], v[148:151], v[196:199], v[72:75]
	v_mfma_f32_16x16x32_bf16 v[108:111], v[144:147], v[176:179], v[108:111]
	v_mfma_f32_16x16x32_bf16 v[104:107], v[152:155], v[176:179], v[104:107]
	v_mfma_f32_16x16x32_bf16 v[124:127], v[144:147], v[184:187], v[124:127]
	v_mfma_f32_16x16x32_bf16 v[120:123], v[152:155], v[184:187], v[120:123]
	v_mfma_f32_16x16x32_bf16 v[92:95], v[144:147], v[192:195], v[92:95]
	v_mfma_f32_16x16x32_bf16 v[88:91], v[152:155], v[192:195], v[88:91]
	v_mfma_f32_16x16x32_bf16 v[76:79], v[144:147], v[200:203], v[76:79]
	v_mfma_f32_16x16x32_bf16 v[72:75], v[152:155], v[200:203], v[72:75]
	s_setprio 0
	s_setprio 1
	v_mfma_f32_16x16x32_bf16 v[100:103], v[156:159], v[172:175], v[100:103]
	v_mfma_f32_16x16x32_bf16 v[96:99], v[164:167], v[172:175], v[96:99]
	v_mfma_f32_16x16x32_bf16 v[116:119], v[156:159], v[180:183], v[116:119]
	v_mfma_f32_16x16x32_bf16 v[112:115], v[164:167], v[180:183], v[112:115]
	v_mfma_f32_16x16x32_bf16 v[84:87], v[156:159], v[188:191], v[84:87]
	v_mfma_f32_16x16x32_bf16 v[80:83], v[164:167], v[188:191], v[80:83]
	v_mfma_f32_16x16x32_bf16 v[68:71], v[156:159], v[196:199], v[68:71]
	v_mfma_f32_16x16x32_bf16 v[64:67], v[164:167], v[196:199], v[64:67]
	v_mfma_f32_16x16x32_bf16 v[100:103], v[160:163], v[176:179], v[100:103]
	v_mfma_f32_16x16x32_bf16 v[96:99], v[168:171], v[176:179], v[96:99]
	v_mfma_f32_16x16x32_bf16 v[116:119], v[160:163], v[184:187], v[116:119]
	v_mfma_f32_16x16x32_bf16 v[112:115], v[168:171], v[184:187], v[112:115]
	v_mfma_f32_16x16x32_bf16 v[84:87], v[160:163], v[192:195], v[84:87]
	v_mfma_f32_16x16x32_bf16 v[80:83], v[168:171], v[192:195], v[80:83]
	v_mfma_f32_16x16x32_bf16 v[68:71], v[160:163], v[200:203], v[68:71]
	v_mfma_f32_16x16x32_bf16 v[64:67], v[168:171], v[200:203], v[64:67]
	s_setprio 0
	s_barrier
	s_add_i32 s28, s80, s49
	v_lshl_add_u64 v[204:205], s[62:63], 0, v[208:209]
	s_mov_b32 m0, s28
	ds_read_b128 v[172:175], v139 offset:16384
	ds_read_b128 v[176:179], v139 offset:17408
	ds_read_b128 v[180:183], v139 offset:18432
	ds_read_b128 v[184:187], v139 offset:19456
	ds_read_b128 v[188:191], v139 offset:20480
	ds_read_b128 v[192:195], v139 offset:21504
	ds_read_b128 v[196:199], v139 offset:22528
	ds_read_b128 v[200:203], v139 offset:23552
	global_load_lds_dwordx4 v208, s[62:63]
	s_add_i32 m0, s28, 0x2000
	s_add_u32 s28, s62, 0x100000
	v_lshl_add_u64 v[206:207], s[62:63], 0, v[128:129]
	s_addc_u32 s29, s63, 0
	s_add_i32 s15, s15, s49
	global_load_lds_dwordx4 v128, s[62:63]
	s_mov_b32 m0, s15
	v_lshl_add_u64 v[212:213], s[36:37], 0, v[128:129]
	global_load_lds_dwordx4 v208, s[28:29]
	s_add_i32 m0, s15, 0x2000
	s_nop 0
	global_load_lds_dwordx4 v128, s[28:29]
	v_lshl_add_u64 v[210:211], s[36:37], 0, v[208:209]
	s_mov_b32 m0, s21
	s_nop 0
	global_load_lds_dwordx4 v208, s[36:37]
	s_mov_b32 m0, s33
	s_nop 0
	global_load_lds_dwordx4 v128, s[36:37]
	s_waitcnt vmcnt(8)
	s_waitcnt lgkmcnt(0)
	s_barrier
	s_setprio 1
	s_waitcnt lgkmcnt(0)
	v_mfma_f32_16x16x32_bf16 v[60:63], v[140:143], v[172:175], v[60:63]
	v_mfma_f32_16x16x32_bf16 v[56:59], v[148:151], v[172:175], v[56:59]
	v_mfma_f32_16x16x32_bf16 v[44:47], v[140:143], v[180:183], v[44:47]
	v_mfma_f32_16x16x32_bf16 v[40:43], v[148:151], v[180:183], v[40:43]
	v_mfma_f32_16x16x32_bf16 v[28:31], v[140:143], v[188:191], v[28:31]
	v_mfma_f32_16x16x32_bf16 v[24:27], v[148:151], v[188:191], v[24:27]
	v_mfma_f32_16x16x32_bf16 v[12:15], v[140:143], v[196:199], v[12:15]
	v_mfma_f32_16x16x32_bf16 v[8:11], v[148:151], v[196:199], v[8:11]
	v_mfma_f32_16x16x32_bf16 v[60:63], v[144:147], v[176:179], v[60:63]
	v_mfma_f32_16x16x32_bf16 v[56:59], v[152:155], v[176:179], v[56:59]
	v_mfma_f32_16x16x32_bf16 v[44:47], v[144:147], v[184:187], v[44:47]
	v_mfma_f32_16x16x32_bf16 v[40:43], v[152:155], v[184:187], v[40:43]
	v_mfma_f32_16x16x32_bf16 v[28:31], v[144:147], v[192:195], v[28:31]
	v_mfma_f32_16x16x32_bf16 v[24:27], v[152:155], v[192:195], v[24:27]
	v_mfma_f32_16x16x32_bf16 v[12:15], v[144:147], v[200:203], v[12:15]
	v_mfma_f32_16x16x32_bf16 v[8:11], v[152:155], v[200:203], v[8:11]
	s_setprio 0
	s_setprio 1
	v_mfma_f32_16x16x32_bf16 v[52:55], v[156:159], v[172:175], v[52:55]
	v_mfma_f32_16x16x32_bf16 v[48:51], v[164:167], v[172:175], v[48:51]
	v_mfma_f32_16x16x32_bf16 v[36:39], v[156:159], v[180:183], v[36:39]
	v_mfma_f32_16x16x32_bf16 v[32:35], v[164:167], v[180:183], v[32:35]
	v_mfma_f32_16x16x32_bf16 v[20:23], v[156:159], v[188:191], v[20:23]
	v_mfma_f32_16x16x32_bf16 v[16:19], v[164:167], v[188:191], v[16:19]
	v_mfma_f32_16x16x32_bf16 v[4:7], v[156:159], v[196:199], v[4:7]
	v_mfma_f32_16x16x32_bf16 v[0:3], v[164:167], v[196:199], v[0:3]
	v_mfma_f32_16x16x32_bf16 v[52:55], v[160:163], v[176:179], v[52:55]
	v_mfma_f32_16x16x32_bf16 v[48:51], v[168:171], v[176:179], v[48:51]
	v_mfma_f32_16x16x32_bf16 v[36:39], v[160:163], v[184:187], v[36:39]
	v_mfma_f32_16x16x32_bf16 v[32:35], v[168:171], v[184:187], v[32:35]
	v_mfma_f32_16x16x32_bf16 v[20:23], v[160:163], v[192:195], v[20:23]
	v_mfma_f32_16x16x32_bf16 v[16:19], v[168:171], v[192:195], v[16:19]
	v_mfma_f32_16x16x32_bf16 v[4:7], v[160:163], v[200:203], v[4:7]
	v_mfma_f32_16x16x32_bf16 v[0:3], v[168:171], v[200:203], v[0:3]
	s_setprio 0
	s_barrier
	s_add_i32 s15, 0, 0x18000
	s_add_i32 s80, 0, 0x1c000
	v_add_u32_e32 v152, s15, v138
	v_add_u32_e32 v168, s80, v138
	ds_read_b128 v[140:143], v152
	ds_read_b128 v[144:147], v152 offset:1024
	ds_read_b128 v[148:151], v152 offset:2048
	ds_read_b128 v[152:155], v152 offset:3072
	ds_read_b128 v[156:159], v168
	ds_read_b128 v[160:163], v168 offset:1024
	ds_read_b128 v[164:167], v168 offset:2048
	ds_read_b128 v[168:171], v168 offset:3072
	s_add_u32 s28, s36, 0x100000
	s_addc_u32 s29, s37, 0
	s_mov_b32 m0, s68
	ds_read_b128 v[172:175], v139 offset:32768
	ds_read_b128 v[176:179], v139 offset:33792
	ds_read_b128 v[180:183], v139 offset:34816
	ds_read_b128 v[184:187], v139 offset:35840
	ds_read_b128 v[188:191], v139 offset:36864
	ds_read_b128 v[192:195], v139 offset:37888
	ds_read_b128 v[196:199], v139 offset:38912
	ds_read_b128 v[200:203], v139 offset:39936
	global_load_lds_dwordx4 v208, s[28:29]
	v_lshl_add_u64 v[224:225], s[28:29], 0, v[128:129]
	s_mov_b32 m0, s69
	s_nop 0
	global_load_lds_dwordx4 v128, s[28:29]
	s_waitcnt vmcnt(8)
	s_waitcnt lgkmcnt(0)
	s_barrier
	s_setprio 1
	s_waitcnt lgkmcnt(0)
	v_mfma_f32_16x16x32_bf16 v[108:111], v[140:143], v[172:175], v[108:111]
	v_mfma_f32_16x16x32_bf16 v[104:107], v[148:151], v[172:175], v[104:107]
	v_mfma_f32_16x16x32_bf16 v[124:127], v[140:143], v[180:183], v[124:127]
	v_mfma_f32_16x16x32_bf16 v[120:123], v[148:151], v[180:183], v[120:123]
	v_mfma_f32_16x16x32_bf16 v[92:95], v[140:143], v[188:191], v[92:95]
	v_mfma_f32_16x16x32_bf16 v[88:91], v[148:151], v[188:191], v[88:91]
	v_mfma_f32_16x16x32_bf16 v[76:79], v[140:143], v[196:199], v[76:79]
	v_mfma_f32_16x16x32_bf16 v[72:75], v[148:151], v[196:199], v[72:75]
	v_mfma_f32_16x16x32_bf16 v[108:111], v[144:147], v[176:179], v[108:111]
	v_mfma_f32_16x16x32_bf16 v[104:107], v[152:155], v[176:179], v[104:107]
	v_mfma_f32_16x16x32_bf16 v[124:127], v[144:147], v[184:187], v[124:127]
	v_mfma_f32_16x16x32_bf16 v[120:123], v[152:155], v[184:187], v[120:123]
	v_mfma_f32_16x16x32_bf16 v[92:95], v[144:147], v[192:195], v[92:95]
	v_mfma_f32_16x16x32_bf16 v[88:91], v[152:155], v[192:195], v[88:91]
	v_mfma_f32_16x16x32_bf16 v[76:79], v[144:147], v[200:203], v[76:79]
	v_mfma_f32_16x16x32_bf16 v[72:75], v[152:155], v[200:203], v[72:75]
	s_setprio 0
	s_setprio 1
	v_mfma_f32_16x16x32_bf16 v[100:103], v[156:159], v[172:175], v[100:103]
	v_mfma_f32_16x16x32_bf16 v[96:99], v[164:167], v[172:175], v[96:99]
	v_mfma_f32_16x16x32_bf16 v[116:119], v[156:159], v[180:183], v[116:119]
	v_mfma_f32_16x16x32_bf16 v[112:115], v[164:167], v[180:183], v[112:115]
	v_mfma_f32_16x16x32_bf16 v[84:87], v[156:159], v[188:191], v[84:87]
	v_mfma_f32_16x16x32_bf16 v[80:83], v[164:167], v[188:191], v[80:83]
	v_mfma_f32_16x16x32_bf16 v[68:71], v[156:159], v[196:199], v[68:71]
	v_mfma_f32_16x16x32_bf16 v[64:67], v[164:167], v[196:199], v[64:67]
	v_mfma_f32_16x16x32_bf16 v[100:103], v[160:163], v[176:179], v[100:103]
	v_mfma_f32_16x16x32_bf16 v[96:99], v[168:171], v[176:179], v[96:99]
	v_mfma_f32_16x16x32_bf16 v[116:119], v[160:163], v[184:187], v[116:119]
	v_mfma_f32_16x16x32_bf16 v[112:115], v[168:171], v[184:187], v[112:115]
	v_mfma_f32_16x16x32_bf16 v[84:87], v[160:163], v[192:195], v[84:87]
	v_mfma_f32_16x16x32_bf16 v[80:83], v[168:171], v[192:195], v[80:83]
	v_mfma_f32_16x16x32_bf16 v[68:71], v[160:163], v[200:203], v[68:71]
	v_mfma_f32_16x16x32_bf16 v[64:67], v[168:171], v[200:203], v[64:67]
	s_setprio 0
	s_barrier
	s_add_i32 s15, s15, s49
	v_lshl_add_u64 v[204:205], v[204:205], 0, s[76:77]
	s_mov_b32 m0, s15
	ds_read_b128 v[172:175], v139 offset:49152
	ds_read_b128 v[176:179], v139 offset:50176
	ds_read_b128 v[180:183], v139 offset:51200
	ds_read_b128 v[184:187], v139 offset:52224
	ds_read_b128 v[188:191], v139 offset:53248
	ds_read_b128 v[192:195], v139 offset:54272
	ds_read_b128 v[196:199], v139 offset:55296
	ds_read_b128 v[200:203], v139 offset:56320
	global_load_lds_dwordx4 v[204:205], off
	s_add_i32 m0, s15, 0x2000
	s_add_u32 s28, s62, 0x100080
	v_lshl_add_u64 v[204:205], v[206:207], 0, s[76:77]
	s_addc_u32 s29, s63, 0
	s_add_i32 s15, s80, s49
	global_load_lds_dwordx4 v[204:205], off
	s_mov_b32 m0, s15
	s_nop 0
	global_load_lds_dwordx4 v208, s[28:29]
	s_add_i32 m0, s15, 0x2000
	s_nop 0
	global_load_lds_dwordx4 v128, s[28:29]
	v_lshl_add_u64 v[204:205], v[210:211], 0, s[76:77]
	s_mov_b32 m0, s17
	s_nop 0
	global_load_lds_dwordx4 v[204:205], off
	v_lshl_add_u64 v[204:205], v[212:213], 0, s[76:77]
	s_mov_b32 m0, s40
	s_nop 0
	global_load_lds_dwordx4 v[204:205], off
	s_waitcnt vmcnt(8)
	s_waitcnt lgkmcnt(0)
	s_barrier
	s_setprio 1
	s_waitcnt lgkmcnt(0)
	v_mfma_f32_16x16x32_bf16 v[60:63], v[140:143], v[172:175], v[60:63]
	v_mfma_f32_16x16x32_bf16 v[56:59], v[148:151], v[172:175], v[56:59]
	v_mfma_f32_16x16x32_bf16 v[44:47], v[140:143], v[180:183], v[44:47]
	v_mfma_f32_16x16x32_bf16 v[40:43], v[148:151], v[180:183], v[40:43]
	v_mfma_f32_16x16x32_bf16 v[28:31], v[140:143], v[188:191], v[28:31]
	v_mfma_f32_16x16x32_bf16 v[24:27], v[148:151], v[188:191], v[24:27]
	v_mfma_f32_16x16x32_bf16 v[12:15], v[140:143], v[196:199], v[12:15]
	v_mfma_f32_16x16x32_bf16 v[8:11], v[148:151], v[196:199], v[8:11]
	v_mfma_f32_16x16x32_bf16 v[60:63], v[144:147], v[176:179], v[60:63]
	v_mfma_f32_16x16x32_bf16 v[56:59], v[152:155], v[176:179], v[56:59]
	v_mfma_f32_16x16x32_bf16 v[44:47], v[144:147], v[184:187], v[44:47]
	v_mfma_f32_16x16x32_bf16 v[40:43], v[152:155], v[184:187], v[40:43]
	v_mfma_f32_16x16x32_bf16 v[28:31], v[144:147], v[192:195], v[28:31]
	v_mfma_f32_16x16x32_bf16 v[24:27], v[152:155], v[192:195], v[24:27]
	v_mfma_f32_16x16x32_bf16 v[12:15], v[144:147], v[200:203], v[12:15]
	v_mfma_f32_16x16x32_bf16 v[8:11], v[152:155], v[200:203], v[8:11]
	s_setprio 0
	s_setprio 1
	v_mfma_f32_16x16x32_bf16 v[52:55], v[156:159], v[172:175], v[52:55]
	v_mfma_f32_16x16x32_bf16 v[48:51], v[164:167], v[172:175], v[48:51]
	v_mfma_f32_16x16x32_bf16 v[36:39], v[156:159], v[180:183], v[36:39]
	v_mfma_f32_16x16x32_bf16 v[32:35], v[164:167], v[180:183], v[32:35]
	v_mfma_f32_16x16x32_bf16 v[20:23], v[156:159], v[188:191], v[20:23]
	v_mfma_f32_16x16x32_bf16 v[16:19], v[164:167], v[188:191], v[16:19]
	v_mfma_f32_16x16x32_bf16 v[4:7], v[156:159], v[196:199], v[4:7]
	v_mfma_f32_16x16x32_bf16 v[0:3], v[164:167], v[196:199], v[0:3]
	v_mfma_f32_16x16x32_bf16 v[52:55], v[160:163], v[176:179], v[52:55]
	v_mfma_f32_16x16x32_bf16 v[48:51], v[168:171], v[176:179], v[48:51]
	v_mfma_f32_16x16x32_bf16 v[36:39], v[160:163], v[184:187], v[36:39]
	v_mfma_f32_16x16x32_bf16 v[32:35], v[168:171], v[184:187], v[32:35]
	v_mfma_f32_16x16x32_bf16 v[20:23], v[160:163], v[192:195], v[20:23]
	v_mfma_f32_16x16x32_bf16 v[16:19], v[168:171], v[192:195], v[16:19]
	v_mfma_f32_16x16x32_bf16 v[4:7], v[160:163], v[200:203], v[4:7]
	v_mfma_f32_16x16x32_bf16 v[0:3], v[168:171], v[200:203], v[0:3]
	s_setprio 0
	s_barrier
	s_add_i32 s14, s14, 2
	s_add_u32 vcc_lo, vcc_lo, 0x100
	s_addc_u32 vcc_hi, vcc_hi, 0
	s_cmp_gt_u32 s14, 61
	s_cbranch_scc0 .LBB0_128
	s_add_u32 s36, s87, 0xffffff00
	s_addc_u32 s37, s64, -1
	s_andn2_b64 vcc, exec, s[10:11]
	s_cbranch_vccnz .LBB0_131
	v_mov_b32_e32 v0, 0
	s_mov_b32 s34, s58
	s_mov_b32 s89, s60
	s_mov_b64 s[12:13], s[18:19]
	s_mov_b32 s41, s86
	v_mov_b32_e32 v1, v0
	v_mov_b32_e32 v2, v0
	v_mov_b32_e32 v3, v0
	v_mov_b32_e32 v4, v0
	v_mov_b32_e32 v5, v0
	v_mov_b32_e32 v6, v0
	v_mov_b32_e32 v7, v0
	v_mov_b32_e32 v16, v0
	v_mov_b32_e32 v17, v0
	v_mov_b32_e32 v18, v0
	v_mov_b32_e32 v19, v0
	v_mov_b32_e32 v20, v0
	v_mov_b32_e32 v21, v0
	v_mov_b32_e32 v22, v0
	v_mov_b32_e32 v23, v0
	v_mov_b32_e32 v32, v0
	v_mov_b32_e32 v33, v0
	v_mov_b32_e32 v34, v0
	v_mov_b32_e32 v35, v0
	v_mov_b32_e32 v36, v0
	v_mov_b32_e32 v37, v0
	v_mov_b32_e32 v38, v0
	v_mov_b32_e32 v39, v0
	v_mov_b32_e32 v48, v0
	v_mov_b32_e32 v49, v0
	v_mov_b32_e32 v50, v0
	v_mov_b32_e32 v51, v0
	v_mov_b32_e32 v52, v0
	v_mov_b32_e32 v53, v0
	v_mov_b32_e32 v54, v0
	v_mov_b32_e32 v55, v0
	v_mov_b32_e32 v8, v0
	v_mov_b32_e32 v9, v0
	v_mov_b32_e32 v10, v0
	v_mov_b32_e32 v11, v0
	v_mov_b32_e32 v12, v0
	v_mov_b32_e32 v13, v0
	v_mov_b32_e32 v14, v0
	v_mov_b32_e32 v15, v0
	v_mov_b32_e32 v24, v0
	v_mov_b32_e32 v25, v0
	v_mov_b32_e32 v26, v0
	v_mov_b32_e32 v27, v0
	v_mov_b32_e32 v28, v0
	v_mov_b32_e32 v29, v0
	v_mov_b32_e32 v30, v0
	v_mov_b32_e32 v31, v0
	v_mov_b32_e32 v40, v0
	v_mov_b32_e32 v41, v0
	v_mov_b32_e32 v42, v0
	v_mov_b32_e32 v43, v0
	v_mov_b32_e32 v44, v0
	v_mov_b32_e32 v45, v0
	v_mov_b32_e32 v46, v0
	v_mov_b32_e32 v47, v0
	v_mov_b32_e32 v56, v0
	v_mov_b32_e32 v57, v0
	v_mov_b32_e32 v58, v0
	v_mov_b32_e32 v59, v0
	v_mov_b32_e32 v60, v0
	v_mov_b32_e32 v61, v0
	v_mov_b32_e32 v62, v0
	v_mov_b32_e32 v63, v0
	v_mov_b32_e32 v64, v0
	v_mov_b32_e32 v65, v0
	v_mov_b32_e32 v66, v0
	v_mov_b32_e32 v67, v0
	v_mov_b32_e32 v68, v0
	v_mov_b32_e32 v69, v0
	v_mov_b32_e32 v70, v0
	v_mov_b32_e32 v71, v0
	v_mov_b32_e32 v80, v0
	v_mov_b32_e32 v81, v0
	v_mov_b32_e32 v82, v0
	v_mov_b32_e32 v83, v0
	v_mov_b32_e32 v84, v0
	v_mov_b32_e32 v85, v0
	v_mov_b32_e32 v86, v0
	v_mov_b32_e32 v87, v0
	v_mov_b32_e32 v112, v0
	v_mov_b32_e32 v113, v0
	v_mov_b32_e32 v114, v0
	v_mov_b32_e32 v115, v0
	v_mov_b32_e32 v116, v0
	v_mov_b32_e32 v117, v0
	v_mov_b32_e32 v118, v0
	v_mov_b32_e32 v119, v0
	v_mov_b32_e32 v96, v0
	v_mov_b32_e32 v97, v0
	v_mov_b32_e32 v98, v0
	v_mov_b32_e32 v99, v0
	v_mov_b32_e32 v100, v0
	v_mov_b32_e32 v101, v0
	v_mov_b32_e32 v102, v0
	v_mov_b32_e32 v103, v0
	v_mov_b32_e32 v72, v0
	v_mov_b32_e32 v73, v0
	v_mov_b32_e32 v74, v0
	v_mov_b32_e32 v75, v0
	v_mov_b32_e32 v76, v0
	v_mov_b32_e32 v77, v0
	v_mov_b32_e32 v78, v0
	v_mov_b32_e32 v79, v0
	v_mov_b32_e32 v88, v0
	v_mov_b32_e32 v89, v0
	v_mov_b32_e32 v90, v0
	v_mov_b32_e32 v91, v0
	v_mov_b32_e32 v92, v0
	v_mov_b32_e32 v93, v0
	v_mov_b32_e32 v94, v0
	v_mov_b32_e32 v95, v0
	v_mov_b32_e32 v120, v0
	v_mov_b32_e32 v121, v0
	v_mov_b32_e32 v122, v0
	v_mov_b32_e32 v123, v0
	v_mov_b32_e32 v124, v0
	v_mov_b32_e32 v125, v0
	v_mov_b32_e32 v126, v0
	v_mov_b32_e32 v127, v0
	v_mov_b32_e32 v104, v0
	v_mov_b32_e32 v105, v0
	v_mov_b32_e32 v106, v0
	v_mov_b32_e32 v107, v0
	v_mov_b32_e32 v108, v0
	v_mov_b32_e32 v109, v0
	v_mov_b32_e32 v110, v0
	v_mov_b32_e32 v111, v0
	s_andn2_b64 vcc, exec, s[8:9]
	s_cbranch_vccnz .LBB0_132
	s_branch .LBB0_133

.LBB0_259:
	v_lshrrev_b32_e32 v15, 1, v222
	v_and_b32_e32 v15, 24, v15
	v_and_b32_e32 v14, 15, v222
	v_lshlrev_b32_e32 v16, 1, v15
	s_waitcnt vmcnt(0)
	v_lshl_or_b32 v140, s9, 6, v14
	v_lshl_or_b32 v14, v14, 6, v16
	v_lshlrev_b32_e32 v16, 2, v222
	s_sext_i32_i16 s87, s4
	s_lshl_b32 s4, s9, 13
	v_and_b32_e32 v16, 32, v16
	v_bitop3_b32 v17, v14, s4, v16 bitop3:0xde
	s_lshl_b32 s4, s8, 5
	s_and_b32 s4, s4, 0x60
	s_add_i32 m0, s17, 0x18000
	v_lshl_add_u64 v[6:7], v[6:7], 0, s[76:77]
	s_lshl_b32 s8, s4, 7
	s_waitcnt vmcnt(2)
	s_barrier
	global_load_lds_dwordx4 v[6:7], off
	v_lshl_add_u64 v[4:5], v[4:5], 0, s[76:77]
	s_add_i32 m0, s17, 0x1a000
	s_add_i32 s65, s17, 0x8000
	s_add_i32 s68, s17, 0xa000
	v_bitop3_b32 v141, s8, v14, v16 bitop3:0xf6
	global_load_lds_dwordx4 v[4:5], off
	v_lshl_add_u64 v[0:1], v[0:1], 0, s[76:77]
	s_mov_b32 m0, s65
	s_add_u32 s8, s58, 0x40080
	global_load_lds_dwordx4 v[0:1], off
	v_lshl_add_u64 v[0:1], v[2:3], 0, s[76:77]
	s_mov_b32 m0, s68
	s_addc_u32 s9, s59, 0
	global_load_lds_dwordx4 v[0:1], off
	s_add_i32 m0, s17, 0x1c000
	s_nop 0
	global_load_lds_dwordx4 v132, s[8:9]
	v_lshl_add_u64 v[0:1], s[8:9], 0, v[128:129]
	s_add_i32 m0, s17, 0x1e000
	s_cmpk_lt_u32 s5, 0x100
	global_load_lds_dwordx4 v128, s[8:9]
	v_lshlrev_b32_e32 v0, 14, v12
	v_and_b32_e32 v0, 0xffff8000, v0
	v_lshl_add_u32 v0, v11, 11, v0
	v_and_b32_e32 v1, 1, v12
	v_lshl_or_b32 v0, v1, 6, v0
	v_lshl_add_u32 v136, v13, 1, v0
	v_lshlrev_b32_e32 v0, 14, v8
	v_and_b32_e32 v0, 0xffff8000, v0
	s_waitcnt vmcnt(6)
	v_lshl_add_u32 v0, v9, 11, v0
	v_and_b32_e32 v1, 1, v8
	v_lshl_or_b32 v0, v1, 6, v0
	s_cselect_b64 s[14:15], -1, 0
	s_waitcnt lgkmcnt(0)
	s_ashr_i32 s69, s6, 31
	v_or_b32_e32 v142, s4, v15
	v_mov_b32_e32 v137, v209
	v_lshl_add_u32 v138, v10, 1, v0
	v_mov_b32_e32 v139, v209
	s_mov_b32 s89, 0
	v_add_u32_e32 v143, 0, v17
	s_barrier
	s_branch .LBB0_262

.LBB0_265:
	s_add_u32 s4, s48, 0xfffc0080
	s_addc_u32 s5, s49, -1
	s_add_i32 s28, 0, 0x10000
	s_cmp_eq_u32 s86, 12
	s_cselect_b32 s37, s31, s5
	s_cselect_b32 s36, vcc_lo, s4
	s_cselect_b32 s5, s19, s59
	s_cselect_b32 s4, vcc_hi, s58
	s_add_i32 s80, 0, 0x14000
	v_add_u32_e32 v156, s28, v141
	v_add_u32_e32 v172, s80, v141
	ds_read_b128 v[144:147], v156
	ds_read_b128 v[148:151], v156 offset:1024
	ds_read_b128 v[152:155], v156 offset:2048
	ds_read_b128 v[156:159], v156 offset:3072
	ds_read_b128 v[160:163], v172
	ds_read_b128 v[164:167], v172 offset:1024
	ds_read_b128 v[168:171], v172 offset:2048
	ds_read_b128 v[172:175], v172 offset:3072
	s_add_i32 m0, s17, 0xc000
	ds_read_b128 v[176:179], v143
	ds_read_b128 v[180:183], v143 offset:1024
	ds_read_b128 v[184:187], v143 offset:2048
	ds_read_b128 v[188:191], v143 offset:3072
	ds_read_b128 v[192:195], v143 offset:4096
	ds_read_b128 v[196:199], v143 offset:5120
	ds_read_b128 v[200:203], v143 offset:6144
	ds_read_b128 v[204:207], v143 offset:7168
	global_load_lds_dwordx4 v136, s[48:49]
	s_add_i32 m0, s17, 0xe000
	s_nop 0
	global_load_lds_dwordx4 v138, s[48:49]
	s_waitcnt vmcnt(8)
	s_waitcnt lgkmcnt(0)
	s_barrier
	s_setprio 1
	s_waitcnt lgkmcnt(0)
	v_mfma_f32_16x16x32_bf16 v[124:127], v[144:147], v[176:179], v[124:127]
	v_mfma_f32_16x16x32_bf16 v[120:123], v[152:155], v[176:179], v[120:123]
	v_mfma_f32_16x16x32_bf16 v[116:119], v[144:147], v[184:187], v[116:119]
	v_mfma_f32_16x16x32_bf16 v[112:115], v[152:155], v[184:187], v[112:115]
	v_mfma_f32_16x16x32_bf16 v[100:103], v[144:147], v[192:195], v[100:103]
	v_mfma_f32_16x16x32_bf16 v[96:99], v[152:155], v[192:195], v[96:99]
	v_mfma_f32_16x16x32_bf16 v[84:87], v[144:147], v[200:203], v[84:87]
	v_mfma_f32_16x16x32_bf16 v[80:83], v[152:155], v[200:203], v[80:83]
	v_mfma_f32_16x16x32_bf16 v[124:127], v[148:151], v[180:183], v[124:127]
	v_mfma_f32_16x16x32_bf16 v[120:123], v[156:159], v[180:183], v[120:123]
	v_mfma_f32_16x16x32_bf16 v[116:119], v[148:151], v[188:191], v[116:119]
	v_mfma_f32_16x16x32_bf16 v[112:115], v[156:159], v[188:191], v[112:115]
	v_mfma_f32_16x16x32_bf16 v[100:103], v[148:151], v[196:199], v[100:103]
	v_mfma_f32_16x16x32_bf16 v[96:99], v[156:159], v[196:199], v[96:99]
	v_mfma_f32_16x16x32_bf16 v[84:87], v[148:151], v[204:207], v[84:87]
	v_mfma_f32_16x16x32_bf16 v[80:83], v[156:159], v[204:207], v[80:83]
	s_setprio 0
	s_setprio 1
	v_mfma_f32_16x16x32_bf16 v[108:111], v[160:163], v[176:179], v[108:111]
	v_mfma_f32_16x16x32_bf16 v[104:107], v[168:171], v[176:179], v[104:107]
	v_mfma_f32_16x16x32_bf16 v[92:95], v[160:163], v[184:187], v[92:95]
	v_mfma_f32_16x16x32_bf16 v[88:91], v[168:171], v[184:187], v[88:91]
	v_mfma_f32_16x16x32_bf16 v[76:79], v[160:163], v[192:195], v[76:79]
	v_mfma_f32_16x16x32_bf16 v[72:75], v[168:171], v[192:195], v[72:75]
	v_mfma_f32_16x16x32_bf16 v[68:71], v[160:163], v[200:203], v[68:71]
	v_mfma_f32_16x16x32_bf16 v[64:67], v[168:171], v[200:203], v[64:67]
	v_mfma_f32_16x16x32_bf16 v[108:111], v[164:167], v[180:183], v[108:111]
	v_mfma_f32_16x16x32_bf16 v[104:107], v[172:175], v[180:183], v[104:107]
	v_mfma_f32_16x16x32_bf16 v[92:95], v[164:167], v[188:191], v[92:95]
	v_mfma_f32_16x16x32_bf16 v[88:91], v[172:175], v[188:191], v[88:91]
	v_mfma_f32_16x16x32_bf16 v[76:79], v[164:167], v[196:199], v[76:79]
	v_mfma_f32_16x16x32_bf16 v[72:75], v[172:175], v[196:199], v[72:75]
	v_mfma_f32_16x16x32_bf16 v[68:71], v[164:167], v[204:207], v[68:71]
	v_mfma_f32_16x16x32_bf16 v[64:67], v[172:175], v[204:207], v[64:67]
	s_setprio 0
	s_barrier
	s_add_i32 s28, s28, s60
	v_lshl_add_u64 v[210:211], s[4:5], 0, v[132:133]
	s_mov_b32 m0, s28
	ds_read_b128 v[176:179], v143 offset:16384
	ds_read_b128 v[180:183], v143 offset:17408
	ds_read_b128 v[184:187], v143 offset:18432
	ds_read_b128 v[188:191], v143 offset:19456
	ds_read_b128 v[192:195], v143 offset:20480
	ds_read_b128 v[196:199], v143 offset:21504
	ds_read_b128 v[200:203], v143 offset:22528
	ds_read_b128 v[204:207], v143 offset:23552
	global_load_lds_dwordx4 v132, s[4:5]
	s_add_i32 m0, s28, 0x2000
	s_add_u32 s28, s4, 0x40000
	v_lshl_add_u64 v[212:213], s[4:5], 0, v[128:129]
	s_addc_u32 s29, s5, 0
	s_add_i32 s80, s80, s60
	global_load_lds_dwordx4 v128, s[4:5]
	s_mov_b32 m0, s80
	v_lshl_add_u64 v[226:227], s[36:37], 0, v[130:131]
	global_load_lds_dwordx4 v132, s[28:29]
	s_add_i32 m0, s80, 0x2000
	s_nop 0
	global_load_lds_dwordx4 v128, s[28:29]
	v_lshl_add_u64 v[224:225], s[36:37], 0, v[134:135]
	s_mov_b32 m0, s17
	s_nop 0
	global_load_lds_dwordx4 v134, s[36:37]
	s_mov_b32 m0, s64
	s_nop 0
	global_load_lds_dwordx4 v130, s[36:37]
	s_waitcnt vmcnt(8)
	s_waitcnt lgkmcnt(0)
	s_barrier
	s_setprio 1
	s_waitcnt lgkmcnt(0)
	v_mfma_f32_16x16x32_bf16 v[60:63], v[144:147], v[176:179], v[60:63]
	v_mfma_f32_16x16x32_bf16 v[56:59], v[152:155], v[176:179], v[56:59]
	v_mfma_f32_16x16x32_bf16 v[52:55], v[144:147], v[184:187], v[52:55]
	v_mfma_f32_16x16x32_bf16 v[48:51], v[152:155], v[184:187], v[48:51]
	v_mfma_f32_16x16x32_bf16 v[36:39], v[144:147], v[192:195], v[36:39]
	v_mfma_f32_16x16x32_bf16 v[32:35], v[152:155], v[192:195], v[32:35]
	v_mfma_f32_16x16x32_bf16 v[20:23], v[144:147], v[200:203], v[20:23]
	v_mfma_f32_16x16x32_bf16 v[16:19], v[152:155], v[200:203], v[16:19]
	v_mfma_f32_16x16x32_bf16 v[60:63], v[148:151], v[180:183], v[60:63]
	v_mfma_f32_16x16x32_bf16 v[56:59], v[156:159], v[180:183], v[56:59]
	v_mfma_f32_16x16x32_bf16 v[52:55], v[148:151], v[188:191], v[52:55]
	v_mfma_f32_16x16x32_bf16 v[48:51], v[156:159], v[188:191], v[48:51]
	v_mfma_f32_16x16x32_bf16 v[36:39], v[148:151], v[196:199], v[36:39]
	v_mfma_f32_16x16x32_bf16 v[32:35], v[156:159], v[196:199], v[32:35]
	v_mfma_f32_16x16x32_bf16 v[20:23], v[148:151], v[204:207], v[20:23]
	v_mfma_f32_16x16x32_bf16 v[16:19], v[156:159], v[204:207], v[16:19]
	s_setprio 0
	s_setprio 1
	v_mfma_f32_16x16x32_bf16 v[44:47], v[160:163], v[176:179], v[44:47]
	v_mfma_f32_16x16x32_bf16 v[40:43], v[168:171], v[176:179], v[40:43]
	v_mfma_f32_16x16x32_bf16 v[28:31], v[160:163], v[184:187], v[28:31]
	v_mfma_f32_16x16x32_bf16 v[24:27], v[168:171], v[184:187], v[24:27]
	v_mfma_f32_16x16x32_bf16 v[12:15], v[160:163], v[192:195], v[12:15]
	v_mfma_f32_16x16x32_bf16 v[8:11], v[168:171], v[192:195], v[8:11]
	v_mfma_f32_16x16x32_bf16 v[4:7], v[160:163], v[200:203], v[4:7]
	v_mfma_f32_16x16x32_bf16 v[0:3], v[168:171], v[200:203], v[0:3]
	v_mfma_f32_16x16x32_bf16 v[44:47], v[164:167], v[180:183], v[44:47]
	v_mfma_f32_16x16x32_bf16 v[40:43], v[172:175], v[180:183], v[40:43]
	v_mfma_f32_16x16x32_bf16 v[28:31], v[164:167], v[188:191], v[28:31]
	v_mfma_f32_16x16x32_bf16 v[24:27], v[172:175], v[188:191], v[24:27]
	v_mfma_f32_16x16x32_bf16 v[12:15], v[164:167], v[196:199], v[12:15]
	v_mfma_f32_16x16x32_bf16 v[8:11], v[172:175], v[196:199], v[8:11]
	v_mfma_f32_16x16x32_bf16 v[4:7], v[164:167], v[204:207], v[4:7]
	v_mfma_f32_16x16x32_bf16 v[0:3], v[172:175], v[204:207], v[0:3]
	s_setprio 0
	s_barrier
	s_add_i32 s80, 0, 0x18000
	s_add_i32 s81, 0, 0x1c000
	v_add_u32_e32 v156, s80, v141
	v_add_u32_e32 v172, s81, v141
	ds_read_b128 v[144:147], v156
	ds_read_b128 v[148:151], v156 offset:1024
	ds_read_b128 v[152:155], v156 offset:2048
	ds_read_b128 v[156:159], v156 offset:3072
	ds_read_b128 v[160:163], v172
	ds_read_b128 v[164:167], v172 offset:1024
	ds_read_b128 v[168:171], v172 offset:2048
	ds_read_b128 v[172:175], v172 offset:3072
	s_add_u32 s28, s36, 0x40000
	s_addc_u32 s29, s37, 0
	s_mov_b32 m0, s21
	ds_read_b128 v[176:179], v143 offset:32768
	ds_read_b128 v[180:183], v143 offset:33792
	ds_read_b128 v[184:187], v143 offset:34816
	ds_read_b128 v[188:191], v143 offset:35840
	ds_read_b128 v[192:195], v143 offset:36864
	ds_read_b128 v[196:199], v143 offset:37888
	ds_read_b128 v[200:203], v143 offset:38912
	ds_read_b128 v[204:207], v143 offset:39936
	global_load_lds_dwordx4 v134, s[28:29]
	v_lshl_add_u64 v[228:229], s[28:29], 0, v[130:131]
	s_mov_b32 m0, s33
	s_nop 0
	global_load_lds_dwordx4 v130, s[28:29]
	s_waitcnt vmcnt(8)
	s_waitcnt lgkmcnt(0)
	s_barrier
	s_setprio 1
	s_waitcnt lgkmcnt(0)
	v_mfma_f32_16x16x32_bf16 v[124:127], v[144:147], v[176:179], v[124:127]
	v_mfma_f32_16x16x32_bf16 v[120:123], v[152:155], v[176:179], v[120:123]
	v_mfma_f32_16x16x32_bf16 v[116:119], v[144:147], v[184:187], v[116:119]
	v_mfma_f32_16x16x32_bf16 v[112:115], v[152:155], v[184:187], v[112:115]
	v_mfma_f32_16x16x32_bf16 v[100:103], v[144:147], v[192:195], v[100:103]
	v_mfma_f32_16x16x32_bf16 v[96:99], v[152:155], v[192:195], v[96:99]
	v_mfma_f32_16x16x32_bf16 v[84:87], v[144:147], v[200:203], v[84:87]
	v_mfma_f32_16x16x32_bf16 v[80:83], v[152:155], v[200:203], v[80:83]
	v_mfma_f32_16x16x32_bf16 v[124:127], v[148:151], v[180:183], v[124:127]
	v_mfma_f32_16x16x32_bf16 v[120:123], v[156:159], v[180:183], v[120:123]
	v_mfma_f32_16x16x32_bf16 v[116:119], v[148:151], v[188:191], v[116:119]
	v_mfma_f32_16x16x32_bf16 v[112:115], v[156:159], v[188:191], v[112:115]
	v_mfma_f32_16x16x32_bf16 v[100:103], v[148:151], v[196:199], v[100:103]
	v_mfma_f32_16x16x32_bf16 v[96:99], v[156:159], v[196:199], v[96:99]
	v_mfma_f32_16x16x32_bf16 v[84:87], v[148:151], v[204:207], v[84:87]
	v_mfma_f32_16x16x32_bf16 v[80:83], v[156:159], v[204:207], v[80:83]
	s_setprio 0
	s_setprio 1
	v_mfma_f32_16x16x32_bf16 v[108:111], v[160:163], v[176:179], v[108:111]
	v_mfma_f32_16x16x32_bf16 v[104:107], v[168:171], v[176:179], v[104:107]
	v_mfma_f32_16x16x32_bf16 v[92:95], v[160:163], v[184:187], v[92:95]
	v_mfma_f32_16x16x32_bf16 v[88:91], v[168:171], v[184:187], v[88:91]
	v_mfma_f32_16x16x32_bf16 v[76:79], v[160:163], v[192:195], v[76:79]
	v_mfma_f32_16x16x32_bf16 v[72:75], v[168:171], v[192:195], v[72:75]
	v_mfma_f32_16x16x32_bf16 v[68:71], v[160:163], v[200:203], v[68:71]
	v_mfma_f32_16x16x32_bf16 v[64:67], v[168:171], v[200:203], v[64:67]
	v_mfma_f32_16x16x32_bf16 v[108:111], v[164:167], v[180:183], v[108:111]
	v_mfma_f32_16x16x32_bf16 v[104:107], v[172:175], v[180:183], v[104:107]
	v_mfma_f32_16x16x32_bf16 v[92:95], v[164:167], v[188:191], v[92:95]
	v_mfma_f32_16x16x32_bf16 v[88:91], v[172:175], v[188:191], v[88:91]
	v_mfma_f32_16x16x32_bf16 v[76:79], v[164:167], v[196:199], v[76:79]
	v_mfma_f32_16x16x32_bf16 v[72:75], v[172:175], v[196:199], v[72:75]
	v_mfma_f32_16x16x32_bf16 v[68:71], v[164:167], v[204:207], v[68:71]
	v_mfma_f32_16x16x32_bf16 v[64:67], v[172:175], v[204:207], v[64:67]
	s_setprio 0
	s_barrier
	s_add_i32 s28, s80, s60
	v_lshl_add_u64 v[210:211], v[210:211], 0, s[76:77]
	s_mov_b32 m0, s28
	ds_read_b128 v[176:179], v143 offset:49152
	ds_read_b128 v[180:183], v143 offset:50176
	ds_read_b128 v[184:187], v143 offset:51200
	ds_read_b128 v[188:191], v143 offset:52224
	ds_read_b128 v[192:195], v143 offset:53248
	ds_read_b128 v[196:199], v143 offset:54272
	ds_read_b128 v[200:203], v143 offset:55296
	ds_read_b128 v[204:207], v143 offset:56320
	global_load_lds_dwordx4 v[210:211], off
	s_add_i32 m0, s28, 0x2000
	s_add_u32 s4, s4, 0x40080
	v_lshl_add_u64 v[210:211], v[212:213], 0, s[76:77]
	s_addc_u32 s5, s5, 0
	s_add_i32 s28, s81, s60
	global_load_lds_dwordx4 v[210:211], off
	s_mov_b32 m0, s28
	s_nop 0
	global_load_lds_dwordx4 v132, s[4:5]
	s_add_i32 m0, s28, 0x2000
	s_nop 0
	global_load_lds_dwordx4 v128, s[4:5]
	v_lshl_add_u64 v[210:211], v[224:225], 0, s[76:77]
	s_mov_b32 m0, s65
	s_nop 0
	global_load_lds_dwordx4 v[210:211], off
	v_lshl_add_u64 v[210:211], v[226:227], 0, s[76:77]
	s_mov_b32 m0, s68
	s_nop 0
	global_load_lds_dwordx4 v[210:211], off
	s_waitcnt vmcnt(8)
	s_waitcnt lgkmcnt(0)
	s_barrier
	s_setprio 1
	s_waitcnt lgkmcnt(0)
	v_mfma_f32_16x16x32_bf16 v[60:63], v[144:147], v[176:179], v[60:63]
	v_mfma_f32_16x16x32_bf16 v[56:59], v[152:155], v[176:179], v[56:59]
	v_mfma_f32_16x16x32_bf16 v[52:55], v[144:147], v[184:187], v[52:55]
	v_mfma_f32_16x16x32_bf16 v[48:51], v[152:155], v[184:187], v[48:51]
	v_mfma_f32_16x16x32_bf16 v[36:39], v[144:147], v[192:195], v[36:39]
	v_mfma_f32_16x16x32_bf16 v[32:35], v[152:155], v[192:195], v[32:35]
	v_mfma_f32_16x16x32_bf16 v[20:23], v[144:147], v[200:203], v[20:23]
	v_mfma_f32_16x16x32_bf16 v[16:19], v[152:155], v[200:203], v[16:19]
	v_mfma_f32_16x16x32_bf16 v[60:63], v[148:151], v[180:183], v[60:63]
	v_mfma_f32_16x16x32_bf16 v[56:59], v[156:159], v[180:183], v[56:59]
	v_mfma_f32_16x16x32_bf16 v[52:55], v[148:151], v[188:191], v[52:55]
	v_mfma_f32_16x16x32_bf16 v[48:51], v[156:159], v[188:191], v[48:51]
	v_mfma_f32_16x16x32_bf16 v[36:39], v[148:151], v[196:199], v[36:39]
	v_mfma_f32_16x16x32_bf16 v[32:35], v[156:159], v[196:199], v[32:35]
	v_mfma_f32_16x16x32_bf16 v[20:23], v[148:151], v[204:207], v[20:23]
	v_mfma_f32_16x16x32_bf16 v[16:19], v[156:159], v[204:207], v[16:19]
	s_setprio 0
	s_setprio 1
	v_mfma_f32_16x16x32_bf16 v[44:47], v[160:163], v[176:179], v[44:47]
	v_mfma_f32_16x16x32_bf16 v[40:43], v[168:171], v[176:179], v[40:43]
	v_mfma_f32_16x16x32_bf16 v[28:31], v[160:163], v[184:187], v[28:31]
	v_mfma_f32_16x16x32_bf16 v[24:27], v[168:171], v[184:187], v[24:27]
	v_mfma_f32_16x16x32_bf16 v[12:15], v[160:163], v[192:195], v[12:15]
	v_mfma_f32_16x16x32_bf16 v[8:11], v[168:171], v[192:195], v[8:11]
	v_mfma_f32_16x16x32_bf16 v[4:7], v[160:163], v[200:203], v[4:7]
	v_mfma_f32_16x16x32_bf16 v[0:3], v[168:171], v[200:203], v[0:3]
	v_mfma_f32_16x16x32_bf16 v[44:47], v[164:167], v[180:183], v[44:47]
	v_mfma_f32_16x16x32_bf16 v[40:43], v[172:175], v[180:183], v[40:43]
	v_mfma_f32_16x16x32_bf16 v[28:31], v[164:167], v[188:191], v[28:31]
	v_mfma_f32_16x16x32_bf16 v[24:27], v[172:175], v[188:191], v[24:27]
	v_mfma_f32_16x16x32_bf16 v[12:15], v[164:167], v[196:199], v[12:15]
	v_mfma_f32_16x16x32_bf16 v[8:11], v[172:175], v[196:199], v[8:11]
	v_mfma_f32_16x16x32_bf16 v[4:7], v[164:167], v[204:207], v[4:7]
	v_mfma_f32_16x16x32_bf16 v[0:3], v[172:175], v[204:207], v[0:3]
	s_setprio 0
	s_barrier
	s_add_i32 s86, s86, 2
	s_add_u32 s48, s48, 0x100
	s_addc_u32 s49, s49, 0
	s_add_u32 s58, s58, 0x100
	s_addc_u32 s59, s59, 0
	s_cmp_gt_u32 s86, 13
	s_cbranch_scc0 .LBB0_265
	s_and_b64 vcc, exec, s[14:15]
	s_cbranch_vccz .LBB0_268
	s_barrier

.LBB0_279:
	v_lshrrev_b32_e32 v15, 1, v222
	v_and_b32_e32 v15, 24, v15
	v_and_b32_e32 v14, 15, v222
	v_lshlrev_b32_e32 v16, 1, v15
	v_lshl_or_b32 v140, s8, 6, v14
	v_lshl_or_b32 v14, v14, 6, v16
	v_lshlrev_b32_e32 v16, 2, v222
	s_lshl_b32 s5, s5, 5
	s_lshl_b32 s8, s8, 13
	v_and_b32_e32 v16, 32, v16
	s_and_b32 s5, s5, 0x60
	s_add_i32 m0, s59, 0x18000
	v_lshl_add_u64 v[6:7], v[6:7], 0, s[76:77]
	v_bitop3_b32 v17, v14, s8, v16 bitop3:0xde
	s_lshl_b32 s8, s5, 7
	s_waitcnt vmcnt(2)
	s_barrier
	global_load_lds_dwordx4 v[6:7], off
	v_lshl_add_u64 v[4:5], v[4:5], 0, s[76:77]
	s_add_i32 m0, s59, 0x1a000
	s_add_i32 s63, s59, 0x8000
	s_add_i32 s64, s59, 0xa000
	v_bitop3_b32 v141, s8, v14, v16 bitop3:0xf6
	global_load_lds_dwordx4 v[4:5], off
	v_lshl_add_u64 v[0:1], v[0:1], 0, s[76:77]
	s_mov_b32 m0, s63
	s_add_u32 s8, s40, 0x40080
	global_load_lds_dwordx4 v[0:1], off
	v_lshl_add_u64 v[0:1], v[2:3], 0, s[76:77]
	s_mov_b32 m0, s64
	s_addc_u32 s9, s41, 0
	global_load_lds_dwordx4 v[0:1], off
	s_add_i32 m0, s59, 0x1c000
	s_nop 0
	global_load_lds_dwordx4 v208, s[8:9]
	v_lshl_add_u64 v[0:1], s[8:9], 0, v[128:129]
	s_add_i32 m0, s59, 0x1e000
	s_cmpk_lt_u32 s4, 0x100
	global_load_lds_dwordx4 v128, s[8:9]
	v_lshlrev_b32_e32 v0, 14, v12
	v_and_b32_e32 v0, 0xffff8000, v0
	v_lshl_add_u32 v0, v11, 11, v0
	v_and_b32_e32 v1, 1, v12
	v_lshl_or_b32 v0, v1, 6, v0
	v_lshl_add_u32 v134, v13, 1, v0
	v_lshlrev_b32_e32 v0, 14, v8
	v_and_b32_e32 v0, 0xffff8000, v0
	s_waitcnt vmcnt(6)
	v_lshl_add_u32 v0, v9, 11, v0
	v_and_b32_e32 v1, 1, v8
	v_or_b32_e32 v142, s5, v15
	v_lshl_or_b32 v0, v1, 6, v0
	v_readlane_b32 s4, v254, 35
	s_cselect_b64 s[12:13], -1, 0
	s_waitcnt lgkmcnt(0)
	s_ashr_i32 s65, s6, 31
	v_mov_b32_e32 v135, v209
	v_lshl_add_u32 v136, v10, 1, v0
	v_mov_b32_e32 v137, v209
	s_mov_b32 s66, 0
	v_add_u32_e32 v143, 0, v17
	v_readlane_b32 s21, v254, 34
	s_mov_b32 s33, s4
	s_barrier
	v_readlane_b32 s5, v254, 36
	s_branch .LBB0_282

.LBB0_289:
	s_add_u32 s4, s34, 0xfffc0080
	s_addc_u32 s5, s35, -1
	s_add_i32 s28, 0, 0x10000
	s_cmp_eq_u32 s87, 12
	s_cselect_b32 s37, s17, s5
	s_cselect_b32 s36, s68, s4
	v_add_u32_e32 v138, s28, v141
	s_cselect_b32 s5, s15, s41
	s_cselect_b32 s4, s69, s40
	s_add_i32 s29, 0, 0x14000
	ds_read_b128 v[144:147], v138
	ds_read_b128 v[148:151], v138 offset:1024
	ds_read_b128 v[152:155], v138 offset:2048
	ds_read_b128 v[156:159], v138 offset:3072
	v_add_u32_e32 v138, s29, v141
	ds_read_b128 v[160:163], v138
	ds_read_b128 v[164:167], v138 offset:1024
	ds_read_b128 v[168:171], v138 offset:2048
	ds_read_b128 v[172:175], v138 offset:3072
	s_add_i32 m0, s59, 0xc000
	ds_read_b128 v[176:179], v143
	ds_read_b128 v[180:183], v143 offset:1024
	ds_read_b128 v[184:187], v143 offset:2048
	ds_read_b128 v[188:191], v143 offset:3072
	ds_read_b128 v[192:195], v143 offset:4096
	ds_read_b128 v[196:199], v143 offset:5120
	ds_read_b128 v[200:203], v143 offset:6144
	ds_read_b128 v[204:207], v143 offset:7168
	global_load_lds_dwordx4 v134, s[34:35]
	s_add_i32 m0, s59, 0xe000
	s_nop 0
	global_load_lds_dwordx4 v136, s[34:35]
	s_waitcnt vmcnt(8)
	s_waitcnt lgkmcnt(0)
	s_barrier
	s_setprio 1
	s_waitcnt lgkmcnt(0)
	v_mfma_f32_16x16x32_bf16 v[124:127], v[144:147], v[176:179], v[124:127]
	v_mfma_f32_16x16x32_bf16 v[120:123], v[152:155], v[176:179], v[120:123]
	v_mfma_f32_16x16x32_bf16 v[108:111], v[144:147], v[184:187], v[108:111]
	v_mfma_f32_16x16x32_bf16 v[104:107], v[152:155], v[184:187], v[104:107]
	v_mfma_f32_16x16x32_bf16 v[92:95], v[144:147], v[192:195], v[92:95]
	v_mfma_f32_16x16x32_bf16 v[88:91], v[152:155], v[192:195], v[88:91]
	v_mfma_f32_16x16x32_bf16 v[76:79], v[144:147], v[200:203], v[76:79]
	v_mfma_f32_16x16x32_bf16 v[72:75], v[152:155], v[200:203], v[72:75]
	v_mfma_f32_16x16x32_bf16 v[124:127], v[148:151], v[180:183], v[124:127]
	v_mfma_f32_16x16x32_bf16 v[120:123], v[156:159], v[180:183], v[120:123]
	v_mfma_f32_16x16x32_bf16 v[108:111], v[148:151], v[188:191], v[108:111]
	v_mfma_f32_16x16x32_bf16 v[104:107], v[156:159], v[188:191], v[104:107]
	v_mfma_f32_16x16x32_bf16 v[92:95], v[148:151], v[196:199], v[92:95]
	v_mfma_f32_16x16x32_bf16 v[88:91], v[156:159], v[196:199], v[88:91]
	v_mfma_f32_16x16x32_bf16 v[76:79], v[148:151], v[204:207], v[76:79]
	v_mfma_f32_16x16x32_bf16 v[72:75], v[156:159], v[204:207], v[72:75]
	s_setprio 0
	s_setprio 1
	v_mfma_f32_16x16x32_bf16 v[116:119], v[160:163], v[176:179], v[116:119]
	v_mfma_f32_16x16x32_bf16 v[112:115], v[168:171], v[176:179], v[112:115]
	v_mfma_f32_16x16x32_bf16 v[100:103], v[160:163], v[184:187], v[100:103]
	v_mfma_f32_16x16x32_bf16 v[96:99], v[168:171], v[184:187], v[96:99]
	v_mfma_f32_16x16x32_bf16 v[84:87], v[160:163], v[192:195], v[84:87]
	v_mfma_f32_16x16x32_bf16 v[80:83], v[168:171], v[192:195], v[80:83]
	v_mfma_f32_16x16x32_bf16 v[68:71], v[160:163], v[200:203], v[68:71]
	v_mfma_f32_16x16x32_bf16 v[64:67], v[168:171], v[200:203], v[64:67]
	v_mfma_f32_16x16x32_bf16 v[116:119], v[164:167], v[180:183], v[116:119]
	v_mfma_f32_16x16x32_bf16 v[112:115], v[172:175], v[180:183], v[112:115]
	v_mfma_f32_16x16x32_bf16 v[100:103], v[164:167], v[188:191], v[100:103]
	v_mfma_f32_16x16x32_bf16 v[96:99], v[172:175], v[188:191], v[96:99]
	v_mfma_f32_16x16x32_bf16 v[84:87], v[164:167], v[196:199], v[84:87]
	v_mfma_f32_16x16x32_bf16 v[80:83], v[172:175], v[196:199], v[80:83]
	v_mfma_f32_16x16x32_bf16 v[68:71], v[164:167], v[204:207], v[68:71]
	v_mfma_f32_16x16x32_bf16 v[64:67], v[172:175], v[204:207], v[64:67]
	s_setprio 0
	s_barrier
	s_add_i32 s28, s28, s58
	v_lshl_add_u64 v[138:139], s[4:5], 0, v[208:209]
	s_mov_b32 m0, s28
	ds_read_b128 v[176:179], v143 offset:16384
	ds_read_b128 v[180:183], v143 offset:17408
	ds_read_b128 v[184:187], v143 offset:18432
	ds_read_b128 v[188:191], v143 offset:19456
	ds_read_b128 v[192:195], v143 offset:20480
	ds_read_b128 v[196:199], v143 offset:21504
	ds_read_b128 v[200:203], v143 offset:22528
	ds_read_b128 v[204:207], v143 offset:23552
	global_load_lds_dwordx4 v208, s[4:5]
	s_add_i32 m0, s28, 0x2000
	s_add_u32 vcc_lo, s4, 0x40000
	v_lshl_add_u64 v[210:211], s[4:5], 0, v[128:129]
	s_addc_u32 vcc_hi, s5, 0
	s_add_i32 s28, s29, s58
	global_load_lds_dwordx4 v128, s[4:5]
	s_mov_b32 m0, s28
	v_lshl_add_u64 v[224:225], s[36:37], 0, v[130:131]
	global_load_lds_dwordx4 v208, vcc
	s_add_i32 m0, s28, 0x2000
	s_nop 0
	global_load_lds_dwordx4 v128, vcc
	v_lshl_add_u64 v[212:213], s[36:37], 0, v[132:133]
	s_mov_b32 m0, s59
	s_nop 0
	global_load_lds_dwordx4 v132, s[36:37]
	s_mov_b32 m0, s60
	s_nop 0
	global_load_lds_dwordx4 v130, s[36:37]
	s_waitcnt vmcnt(8)
	s_waitcnt lgkmcnt(0)
	s_barrier
	s_setprio 1
	s_waitcnt lgkmcnt(0)
	v_mfma_f32_16x16x32_bf16 v[60:63], v[144:147], v[176:179], v[60:63]
	v_mfma_f32_16x16x32_bf16 v[56:59], v[152:155], v[176:179], v[56:59]
	v_mfma_f32_16x16x32_bf16 v[44:47], v[144:147], v[184:187], v[44:47]
	v_mfma_f32_16x16x32_bf16 v[40:43], v[152:155], v[184:187], v[40:43]
	v_mfma_f32_16x16x32_bf16 v[28:31], v[144:147], v[192:195], v[28:31]
	v_mfma_f32_16x16x32_bf16 v[24:27], v[152:155], v[192:195], v[24:27]
	v_mfma_f32_16x16x32_bf16 v[12:15], v[144:147], v[200:203], v[12:15]
	v_mfma_f32_16x16x32_bf16 v[8:11], v[152:155], v[200:203], v[8:11]
	v_mfma_f32_16x16x32_bf16 v[60:63], v[148:151], v[180:183], v[60:63]
	v_mfma_f32_16x16x32_bf16 v[56:59], v[156:159], v[180:183], v[56:59]
	v_mfma_f32_16x16x32_bf16 v[44:47], v[148:151], v[188:191], v[44:47]
	v_mfma_f32_16x16x32_bf16 v[40:43], v[156:159], v[188:191], v[40:43]
	v_mfma_f32_16x16x32_bf16 v[28:31], v[148:151], v[196:199], v[28:31]
	v_mfma_f32_16x16x32_bf16 v[24:27], v[156:159], v[196:199], v[24:27]
	v_mfma_f32_16x16x32_bf16 v[12:15], v[148:151], v[204:207], v[12:15]
	v_mfma_f32_16x16x32_bf16 v[8:11], v[156:159], v[204:207], v[8:11]
	s_setprio 0
	s_setprio 1
	v_mfma_f32_16x16x32_bf16 v[52:55], v[160:163], v[176:179], v[52:55]
	v_mfma_f32_16x16x32_bf16 v[48:51], v[168:171], v[176:179], v[48:51]
	v_mfma_f32_16x16x32_bf16 v[36:39], v[160:163], v[184:187], v[36:39]
	v_mfma_f32_16x16x32_bf16 v[32:35], v[168:171], v[184:187], v[32:35]
	v_mfma_f32_16x16x32_bf16 v[20:23], v[160:163], v[192:195], v[20:23]
	v_mfma_f32_16x16x32_bf16 v[16:19], v[168:171], v[192:195], v[16:19]
	v_mfma_f32_16x16x32_bf16 v[4:7], v[160:163], v[200:203], v[4:7]
	v_mfma_f32_16x16x32_bf16 v[0:3], v[168:171], v[200:203], v[0:3]
	v_mfma_f32_16x16x32_bf16 v[52:55], v[164:167], v[180:183], v[52:55]
	v_mfma_f32_16x16x32_bf16 v[48:51], v[172:175], v[180:183], v[48:51]
	v_mfma_f32_16x16x32_bf16 v[36:39], v[164:167], v[188:191], v[36:39]
	v_mfma_f32_16x16x32_bf16 v[32:35], v[172:175], v[188:191], v[32:35]
	v_mfma_f32_16x16x32_bf16 v[20:23], v[164:167], v[196:199], v[20:23]
	v_mfma_f32_16x16x32_bf16 v[16:19], v[172:175], v[196:199], v[16:19]
	v_mfma_f32_16x16x32_bf16 v[4:7], v[164:167], v[204:207], v[4:7]
	v_mfma_f32_16x16x32_bf16 v[0:3], v[172:175], v[204:207], v[0:3]
	s_setprio 0
	s_barrier
	s_add_i32 s28, 0, 0x18000
	s_add_i32 s29, 0, 0x1c000
	v_add_u32_e32 v156, s28, v141
	v_add_u32_e32 v172, s29, v141
	ds_read_b128 v[144:147], v156
	ds_read_b128 v[148:151], v156 offset:1024
	ds_read_b128 v[152:155], v156 offset:2048
	ds_read_b128 v[156:159], v156 offset:3072
	ds_read_b128 v[160:163], v172
	ds_read_b128 v[164:167], v172 offset:1024
	ds_read_b128 v[168:171], v172 offset:2048
	ds_read_b128 v[172:175], v172 offset:3072
	s_add_u32 s36, s36, 0x40000
	s_addc_u32 s37, s37, 0
	s_mov_b32 m0, s61
	ds_read_b128 v[176:179], v143 offset:32768
	ds_read_b128 v[180:183], v143 offset:33792
	ds_read_b128 v[184:187], v143 offset:34816
	ds_read_b128 v[188:191], v143 offset:35840
	ds_read_b128 v[192:195], v143 offset:36864
	ds_read_b128 v[196:199], v143 offset:37888
	ds_read_b128 v[200:203], v143 offset:38912
	ds_read_b128 v[204:207], v143 offset:39936
	global_load_lds_dwordx4 v132, s[36:37]
	v_lshl_add_u64 v[226:227], s[36:37], 0, v[130:131]
	s_mov_b32 m0, s62
	s_nop 0
	global_load_lds_dwordx4 v130, s[36:37]
	s_waitcnt vmcnt(8)
	s_waitcnt lgkmcnt(0)
	s_barrier
	s_setprio 1
	s_waitcnt lgkmcnt(0)
	v_mfma_f32_16x16x32_bf16 v[124:127], v[144:147], v[176:179], v[124:127]
	v_mfma_f32_16x16x32_bf16 v[120:123], v[152:155], v[176:179], v[120:123]
	v_mfma_f32_16x16x32_bf16 v[108:111], v[144:147], v[184:187], v[108:111]
	v_mfma_f32_16x16x32_bf16 v[104:107], v[152:155], v[184:187], v[104:107]
	v_mfma_f32_16x16x32_bf16 v[92:95], v[144:147], v[192:195], v[92:95]
	v_mfma_f32_16x16x32_bf16 v[88:91], v[152:155], v[192:195], v[88:91]
	v_mfma_f32_16x16x32_bf16 v[76:79], v[144:147], v[200:203], v[76:79]
	v_mfma_f32_16x16x32_bf16 v[72:75], v[152:155], v[200:203], v[72:75]
	v_mfma_f32_16x16x32_bf16 v[124:127], v[148:151], v[180:183], v[124:127]
	v_mfma_f32_16x16x32_bf16 v[120:123], v[156:159], v[180:183], v[120:123]
	v_mfma_f32_16x16x32_bf16 v[108:111], v[148:151], v[188:191], v[108:111]
	v_mfma_f32_16x16x32_bf16 v[104:107], v[156:159], v[188:191], v[104:107]
	v_mfma_f32_16x16x32_bf16 v[92:95], v[148:151], v[196:199], v[92:95]
	v_mfma_f32_16x16x32_bf16 v[88:91], v[156:159], v[196:199], v[88:91]
	v_mfma_f32_16x16x32_bf16 v[76:79], v[148:151], v[204:207], v[76:79]
	v_mfma_f32_16x16x32_bf16 v[72:75], v[156:159], v[204:207], v[72:75]
	s_setprio 0
	s_setprio 1
	v_mfma_f32_16x16x32_bf16 v[116:119], v[160:163], v[176:179], v[116:119]
	v_mfma_f32_16x16x32_bf16 v[112:115], v[168:171], v[176:179], v[112:115]
	v_mfma_f32_16x16x32_bf16 v[100:103], v[160:163], v[184:187], v[100:103]
	v_mfma_f32_16x16x32_bf16 v[96:99], v[168:171], v[184:187], v[96:99]
	v_mfma_f32_16x16x32_bf16 v[84:87], v[160:163], v[192:195], v[84:87]
	v_mfma_f32_16x16x32_bf16 v[80:83], v[168:171], v[192:195], v[80:83]
	v_mfma_f32_16x16x32_bf16 v[68:71], v[160:163], v[200:203], v[68:71]
	v_mfma_f32_16x16x32_bf16 v[64:67], v[168:171], v[200:203], v[64:67]
	v_mfma_f32_16x16x32_bf16 v[116:119], v[164:167], v[180:183], v[116:119]
	v_mfma_f32_16x16x32_bf16 v[112:115], v[172:175], v[180:183], v[112:115]
	v_mfma_f32_16x16x32_bf16 v[100:103], v[164:167], v[188:191], v[100:103]
	v_mfma_f32_16x16x32_bf16 v[96:99], v[172:175], v[188:191], v[96:99]
	v_mfma_f32_16x16x32_bf16 v[84:87], v[164:167], v[196:199], v[84:87]
	v_mfma_f32_16x16x32_bf16 v[80:83], v[172:175], v[196:199], v[80:83]
	v_mfma_f32_16x16x32_bf16 v[68:71], v[164:167], v[204:207], v[68:71]
	v_mfma_f32_16x16x32_bf16 v[64:67], v[172:175], v[204:207], v[64:67]
	s_setprio 0
	s_barrier
	s_add_i32 s28, s28, s58
	v_lshl_add_u64 v[138:139], v[138:139], 0, s[76:77]
	s_mov_b32 m0, s28
	ds_read_b128 v[176:179], v143 offset:49152
	ds_read_b128 v[180:183], v143 offset:50176
	ds_read_b128 v[184:187], v143 offset:51200
	ds_read_b128 v[188:191], v143 offset:52224
	ds_read_b128 v[192:195], v143 offset:53248
	ds_read_b128 v[196:199], v143 offset:54272
	ds_read_b128 v[200:203], v143 offset:55296
	ds_read_b128 v[204:207], v143 offset:56320
	global_load_lds_dwordx4 v[138:139], off
	s_add_i32 m0, s28, 0x2000
	s_add_u32 s4, s4, 0x40080
	v_lshl_add_u64 v[138:139], v[210:211], 0, s[76:77]
	s_addc_u32 s5, s5, 0
	s_add_i32 s28, s29, s58
	global_load_lds_dwordx4 v[138:139], off
	s_mov_b32 m0, s28
	s_nop 0
	global_load_lds_dwordx4 v208, s[4:5]
	s_add_i32 m0, s28, 0x2000
	s_nop 0
	global_load_lds_dwordx4 v128, s[4:5]
	v_lshl_add_u64 v[138:139], v[212:213], 0, s[76:77]
	s_mov_b32 m0, s63
	s_nop 0
	global_load_lds_dwordx4 v[138:139], off
	v_lshl_add_u64 v[138:139], v[224:225], 0, s[76:77]
	s_mov_b32 m0, s64
	s_nop 0
	global_load_lds_dwordx4 v[138:139], off
	s_waitcnt vmcnt(8)
	s_waitcnt lgkmcnt(0)
	s_barrier
	s_setprio 1
	s_waitcnt lgkmcnt(0)
	v_mfma_f32_16x16x32_bf16 v[60:63], v[144:147], v[176:179], v[60:63]
	v_mfma_f32_16x16x32_bf16 v[56:59], v[152:155], v[176:179], v[56:59]
	v_mfma_f32_16x16x32_bf16 v[44:47], v[144:147], v[184:187], v[44:47]
	v_mfma_f32_16x16x32_bf16 v[40:43], v[152:155], v[184:187], v[40:43]
	v_mfma_f32_16x16x32_bf16 v[28:31], v[144:147], v[192:195], v[28:31]
	v_mfma_f32_16x16x32_bf16 v[24:27], v[152:155], v[192:195], v[24:27]
	v_mfma_f32_16x16x32_bf16 v[12:15], v[144:147], v[200:203], v[12:15]
	v_mfma_f32_16x16x32_bf16 v[8:11], v[152:155], v[200:203], v[8:11]
	v_mfma_f32_16x16x32_bf16 v[60:63], v[148:151], v[180:183], v[60:63]
	v_mfma_f32_16x16x32_bf16 v[56:59], v[156:159], v[180:183], v[56:59]
	v_mfma_f32_16x16x32_bf16 v[44:47], v[148:151], v[188:191], v[44:47]
	v_mfma_f32_16x16x32_bf16 v[40:43], v[156:159], v[188:191], v[40:43]
	v_mfma_f32_16x16x32_bf16 v[28:31], v[148:151], v[196:199], v[28:31]
	v_mfma_f32_16x16x32_bf16 v[24:27], v[156:159], v[196:199], v[24:27]
	v_mfma_f32_16x16x32_bf16 v[12:15], v[148:151], v[204:207], v[12:15]
	v_mfma_f32_16x16x32_bf16 v[8:11], v[156:159], v[204:207], v[8:11]
	s_setprio 0
	s_setprio 1
	v_mfma_f32_16x16x32_bf16 v[52:55], v[160:163], v[176:179], v[52:55]
	v_mfma_f32_16x16x32_bf16 v[48:51], v[168:171], v[176:179], v[48:51]
	v_mfma_f32_16x16x32_bf16 v[36:39], v[160:163], v[184:187], v[36:39]
	v_mfma_f32_16x16x32_bf16 v[32:35], v[168:171], v[184:187], v[32:35]
	v_mfma_f32_16x16x32_bf16 v[20:23], v[160:163], v[192:195], v[20:23]
	v_mfma_f32_16x16x32_bf16 v[16:19], v[168:171], v[192:195], v[16:19]
	v_mfma_f32_16x16x32_bf16 v[4:7], v[160:163], v[200:203], v[4:7]
	v_mfma_f32_16x16x32_bf16 v[0:3], v[168:171], v[200:203], v[0:3]
	v_mfma_f32_16x16x32_bf16 v[52:55], v[164:167], v[180:183], v[52:55]
	v_mfma_f32_16x16x32_bf16 v[48:51], v[172:175], v[180:183], v[48:51]
	v_mfma_f32_16x16x32_bf16 v[36:39], v[164:167], v[188:191], v[36:39]
	v_mfma_f32_16x16x32_bf16 v[32:35], v[172:175], v[188:191], v[32:35]
	v_mfma_f32_16x16x32_bf16 v[20:23], v[164:167], v[196:199], v[20:23]
	v_mfma_f32_16x16x32_bf16 v[16:19], v[172:175], v[196:199], v[16:19]
	v_mfma_f32_16x16x32_bf16 v[4:7], v[164:167], v[204:207], v[4:7]
	v_mfma_f32_16x16x32_bf16 v[0:3], v[172:175], v[204:207], v[0:3]
	s_setprio 0
	s_barrier
	s_add_i32 s87, s87, 2
	s_add_u32 s34, s34, 0x100
	s_addc_u32 s35, s35, 0
	s_add_u32 s40, s40, 0x100
	s_addc_u32 s41, s41, 0
	s_cmp_gt_u32 s87, 13
	s_cbranch_scc0 .LBB0_289
	s_and_b64 vcc, exec, s[12:13]
	s_cbranch_vccz .LBB0_292
	s_barrier

.LBB0_378:
	s_lshl_b32 s7, s7, 13
	s_add_u32 s14, s90, s7
	s_addc_u32 s15, s91, 0
	s_lshl_b32 s7, s16, 5
	s_and_b32 s21, s7, 0x60
	s_add_i32 m0, s37, 0x18000
	v_lshl_add_u64 v[6:7], v[6:7], 0, s[76:77]
	s_lshl_b32 s18, s9, 13
	s_lshl_b32 s19, s21, 7
	s_waitcnt vmcnt(2)
	s_barrier
	global_load_lds_dwordx4 v[6:7], off
	v_lshl_add_u64 v[4:5], v[4:5], 0, s[76:77]
	s_add_i32 m0, s37, 0x1a000
	s_add_i32 s7, s37, 0x8000
	s_add_i32 s58, s37, 0xa000
	global_load_lds_dwordx4 v[4:5], off
	v_lshl_add_u64 v[0:1], v[0:1], 0, s[76:77]
	s_mov_b32 m0, s7
	s_add_u32 s16, s4, 0x40080
	global_load_lds_dwordx4 v[0:1], off
	v_lshl_add_u64 v[0:1], v[2:3], 0, s[76:77]
	s_mov_b32 m0, s58
	s_addc_u32 s17, s5, 0
	global_load_lds_dwordx4 v[0:1], off
	s_add_i32 m0, s37, 0x1c000
	s_nop 0
	global_load_lds_dwordx4 v148, s[16:17]
	v_lshl_add_u64 v[0:1], s[16:17], 0, v[144:145]
	s_add_i32 m0, s37, 0x1e000
	s_cmpk_lt_u32 s8, 0x100
	global_load_lds_dwordx4 v144, s[16:17]
	v_lshrrev_b32_e32 v1, 1, v222
	v_and_b32_e32 v1, 24, v1
	v_and_b32_e32 v0, 15, v222
	v_lshlrev_b32_e32 v2, 1, v1
	v_lshl_or_b32 v162, s9, 6, v0
	v_lshl_or_b32 v0, v0, 6, v2
	v_lshlrev_b32_e32 v2, 2, v222
	v_and_b32_e32 v2, 32, v2
	v_bitop3_b32 v3, v0, s18, v2 bitop3:0xde
	v_bitop3_b32 v163, s19, v0, v2 bitop3:0xf6
	v_lshlrev_b32_e32 v0, 14, v12
	v_and_b32_e32 v0, 0xffff8000, v0
	v_or_b32_e32 v164, s21, v1
	v_lshl_add_u32 v0, v11, 11, v0
	v_and_b32_e32 v1, 1, v12
	v_lshl_or_b32 v0, v1, 6, v0
	v_lshl_add_u32 v152, v13, 1, v0
	v_lshlrev_b32_e32 v0, 14, v8
	v_and_b32_e32 v0, 0xffff8000, v0
	s_waitcnt vmcnt(6)
	v_lshl_add_u32 v0, v9, 11, v0
	v_and_b32_e32 v1, 1, v8
	s_cselect_b64 s[16:17], -1, 0
	s_add_u32 s18, s90, 0xbc00000
	v_lshl_or_b32 v0, v1, 6, v0
	v_readlane_b32 s8, v254, 35
	s_addc_u32 s19, s91, 0
	s_waitcnt lgkmcnt(0)
	s_ashr_i32 s59, s6, 31
	v_mov_b32_e32 v153, v209
	v_lshl_add_u32 v154, v10, 1, v0
	v_mov_b32_e32 v155, v209
	s_mov_b32 s60, 0
	v_add_u32_e32 v165, 0, v3
	v_readlane_b32 s21, v254, 34
	s_mov_b32 s33, s8
	s_barrier
	v_readlane_b32 s9, v254, 36
	s_branch .LBB0_381

.LBB0_388:
	s_add_u32 s4, s10, 0xfffc0080
	s_addc_u32 s5, s11, -1
	s_add_i32 s28, 0, 0x10000
	s_cmp_eq_u32 s68, 12
	s_cselect_b32 s35, s31, s5
	s_cselect_b32 s34, s61, s4
	s_cselect_b32 s5, s47, s66
	s_cselect_b32 s4, s62, s63
	s_add_i32 s29, 0, 0x14000
	v_add_u32_e32 v100, s28, v163
	v_add_u32_e32 v160, s29, v163
	ds_read_b128 v[84:87], v100
	ds_read_b128 v[88:91], v100 offset:1024
	ds_read_b128 v[96:99], v100 offset:2048
	ds_read_b128 v[100:103], v100 offset:3072
	ds_read_b128 v[156:159], v160
	ds_read_b128 v[166:169], v160 offset:1024
	ds_read_b128 v[170:173], v160 offset:2048
	ds_read_b128 v[174:177], v160 offset:3072
	s_add_i32 m0, s37, 0xc000
	ds_read_b128 v[178:181], v165
	ds_read_b128 v[182:185], v165 offset:1024
	ds_read_b128 v[186:189], v165 offset:2048
	ds_read_b128 v[190:193], v165 offset:3072
	ds_read_b128 v[194:197], v165 offset:4096
	ds_read_b128 v[198:201], v165 offset:5120
	ds_read_b128 v[202:205], v165 offset:6144
	ds_read_b128 v[224:227], v165 offset:7168
	global_load_lds_dwordx4 v152, s[10:11]
	s_add_i32 m0, s37, 0xe000
	s_nop 0
	global_load_lds_dwordx4 v154, s[10:11]
	s_waitcnt vmcnt(8)
	s_waitcnt lgkmcnt(0)
	s_barrier
	s_setprio 1
	s_waitcnt lgkmcnt(0)
	v_mfma_f32_16x16x32_bf16 v[140:143], v[84:87], v[178:181], v[140:143]
	v_mfma_f32_16x16x32_bf16 v[136:139], v[96:99], v[178:181], v[136:139]
	v_mfma_f32_16x16x32_bf16 v[132:135], v[84:87], v[186:189], v[132:135]
	v_mfma_f32_16x16x32_bf16 v[128:131], v[96:99], v[186:189], v[128:131]
	v_mfma_f32_16x16x32_bf16 v[124:127], v[84:87], v[194:197], v[124:127]
	v_mfma_f32_16x16x32_bf16 v[120:123], v[96:99], v[194:197], v[120:123]
	v_mfma_f32_16x16x32_bf16 v[116:119], v[84:87], v[202:205], v[116:119]
	v_mfma_f32_16x16x32_bf16 v[112:115], v[96:99], v[202:205], v[112:115]
	v_mfma_f32_16x16x32_bf16 v[140:143], v[88:91], v[182:185], v[140:143]
	v_mfma_f32_16x16x32_bf16 v[136:139], v[100:103], v[182:185], v[136:139]
	v_mfma_f32_16x16x32_bf16 v[132:135], v[88:91], v[190:193], v[132:135]
	v_mfma_f32_16x16x32_bf16 v[128:131], v[100:103], v[190:193], v[128:131]
	v_mfma_f32_16x16x32_bf16 v[124:127], v[88:91], v[198:201], v[124:127]
	v_mfma_f32_16x16x32_bf16 v[120:123], v[100:103], v[198:201], v[120:123]
	v_mfma_f32_16x16x32_bf16 v[116:119], v[88:91], v[224:227], v[116:119]
	v_mfma_f32_16x16x32_bf16 v[112:115], v[100:103], v[224:227], v[112:115]
	s_setprio 0
	s_setprio 1
	v_mfma_f32_16x16x32_bf16 v[60:63], v[156:159], v[178:181], v[60:63]
	v_mfma_f32_16x16x32_bf16 v[56:59], v[170:173], v[178:181], v[56:59]
	v_mfma_f32_16x16x32_bf16 v[52:55], v[156:159], v[186:189], v[52:55]
	v_mfma_f32_16x16x32_bf16 v[48:51], v[170:173], v[186:189], v[48:51]
	v_mfma_f32_16x16x32_bf16 v[44:47], v[156:159], v[194:197], v[44:47]
	v_mfma_f32_16x16x32_bf16 v[40:43], v[170:173], v[194:197], v[40:43]
	v_mfma_f32_16x16x32_bf16 v[36:39], v[156:159], v[202:205], v[36:39]
	v_mfma_f32_16x16x32_bf16 v[32:35], v[170:173], v[202:205], v[32:35]
	v_mfma_f32_16x16x32_bf16 v[60:63], v[166:169], v[182:185], v[60:63]
	v_mfma_f32_16x16x32_bf16 v[56:59], v[174:177], v[182:185], v[56:59]
	v_mfma_f32_16x16x32_bf16 v[52:55], v[166:169], v[190:193], v[52:55]
	v_mfma_f32_16x16x32_bf16 v[48:51], v[174:177], v[190:193], v[48:51]
	v_mfma_f32_16x16x32_bf16 v[44:47], v[166:169], v[198:201], v[44:47]
	v_mfma_f32_16x16x32_bf16 v[40:43], v[174:177], v[198:201], v[40:43]
	v_mfma_f32_16x16x32_bf16 v[36:39], v[166:169], v[224:227], v[36:39]
	v_mfma_f32_16x16x32_bf16 v[32:35], v[174:177], v[224:227], v[32:35]
	s_setprio 0
	s_barrier
	s_add_i32 s28, s28, s36
	v_lshl_add_u64 v[160:161], s[4:5], 0, v[148:149]
	s_mov_b32 m0, s28
	ds_read_b128 v[178:181], v165 offset:16384
	ds_read_b128 v[182:185], v165 offset:17408
	ds_read_b128 v[186:189], v165 offset:18432
	ds_read_b128 v[190:193], v165 offset:19456
	ds_read_b128 v[194:197], v165 offset:20480
	ds_read_b128 v[198:201], v165 offset:21504
	ds_read_b128 v[202:205], v165 offset:22528
	ds_read_b128 v[224:227], v165 offset:23552
	global_load_lds_dwordx4 v148, s[4:5]
	s_add_i32 m0, s28, 0x2000
	s_add_u32 s72, s4, 0x40000
	v_lshl_add_u64 v[206:207], s[4:5], 0, v[144:145]
	s_addc_u32 s73, s5, 0
	s_add_i32 s28, s29, s36
	global_load_lds_dwordx4 v144, s[4:5]
	s_mov_b32 m0, s28
	v_lshl_add_u64 v[212:213], s[34:35], 0, v[146:147]
	global_load_lds_dwordx4 v148, s[72:73]
	s_add_i32 m0, s28, 0x2000
	s_nop 0
	global_load_lds_dwordx4 v144, s[72:73]
	v_lshl_add_u64 v[210:211], s[34:35], 0, v[150:151]
	s_mov_b32 m0, s37
	s_nop 0
	global_load_lds_dwordx4 v150, s[34:35]
	s_mov_b32 m0, s48
	s_nop 0
	global_load_lds_dwordx4 v146, s[34:35]
	s_waitcnt vmcnt(8)
	s_waitcnt lgkmcnt(0)
	s_barrier
	s_setprio 1
	s_waitcnt lgkmcnt(0)
	v_mfma_f32_16x16x32_bf16 v[108:111], v[84:87], v[178:181], v[108:111]
	v_mfma_f32_16x16x32_bf16 v[104:107], v[96:99], v[178:181], v[104:107]
	v_mfma_f32_16x16x32_bf16 v[92:95], v[84:87], v[186:189], v[92:95]
	v_mfma_f32_16x16x32_bf16 v[80:83], v[96:99], v[186:189], v[80:83]
	v_mfma_f32_16x16x32_bf16 v[76:79], v[84:87], v[194:197], v[76:79]
	v_mfma_f32_16x16x32_bf16 v[72:75], v[96:99], v[194:197], v[72:75]
	v_mfma_f32_16x16x32_bf16 v[68:71], v[84:87], v[202:205], v[68:71]
	v_mfma_f32_16x16x32_bf16 v[64:67], v[96:99], v[202:205], v[64:67]
	v_mfma_f32_16x16x32_bf16 v[108:111], v[88:91], v[182:185], v[108:111]
	v_mfma_f32_16x16x32_bf16 v[104:107], v[100:103], v[182:185], v[104:107]
	v_mfma_f32_16x16x32_bf16 v[92:95], v[88:91], v[190:193], v[92:95]
	v_mfma_f32_16x16x32_bf16 v[80:83], v[100:103], v[190:193], v[80:83]
	v_mfma_f32_16x16x32_bf16 v[76:79], v[88:91], v[198:201], v[76:79]
	v_mfma_f32_16x16x32_bf16 v[72:75], v[100:103], v[198:201], v[72:75]
	v_mfma_f32_16x16x32_bf16 v[68:71], v[88:91], v[224:227], v[68:71]
	v_mfma_f32_16x16x32_bf16 v[64:67], v[100:103], v[224:227], v[64:67]
	s_setprio 0
	s_setprio 1
	v_mfma_f32_16x16x32_bf16 v[28:31], v[156:159], v[178:181], v[28:31]
	v_mfma_f32_16x16x32_bf16 v[24:27], v[170:173], v[178:181], v[24:27]
	v_mfma_f32_16x16x32_bf16 v[20:23], v[156:159], v[186:189], v[20:23]
	v_mfma_f32_16x16x32_bf16 v[16:19], v[170:173], v[186:189], v[16:19]
	v_mfma_f32_16x16x32_bf16 v[12:15], v[156:159], v[194:197], v[12:15]
	v_mfma_f32_16x16x32_bf16 v[8:11], v[170:173], v[194:197], v[8:11]
	v_mfma_f32_16x16x32_bf16 v[4:7], v[156:159], v[202:205], v[4:7]
	v_mfma_f32_16x16x32_bf16 v[0:3], v[170:173], v[202:205], v[0:3]
	v_mfma_f32_16x16x32_bf16 v[28:31], v[166:169], v[182:185], v[28:31]
	v_mfma_f32_16x16x32_bf16 v[24:27], v[174:177], v[182:185], v[24:27]
	v_mfma_f32_16x16x32_bf16 v[20:23], v[166:169], v[190:193], v[20:23]
	v_mfma_f32_16x16x32_bf16 v[16:19], v[174:177], v[190:193], v[16:19]
	v_mfma_f32_16x16x32_bf16 v[12:15], v[166:169], v[198:201], v[12:15]
	v_mfma_f32_16x16x32_bf16 v[8:11], v[174:177], v[198:201], v[8:11]
	v_mfma_f32_16x16x32_bf16 v[4:7], v[166:169], v[224:227], v[4:7]
	v_mfma_f32_16x16x32_bf16 v[0:3], v[174:177], v[224:227], v[0:3]
	s_setprio 0
	s_barrier
	s_add_i32 s28, 0, 0x18000
	s_add_i32 s29, 0, 0x1c000
	v_add_u32_e32 v100, s28, v163
	v_add_u32_e32 v174, s29, v163
	ds_read_b128 v[84:87], v100
	ds_read_b128 v[88:91], v100 offset:1024
	ds_read_b128 v[96:99], v100 offset:2048
	ds_read_b128 v[100:103], v100 offset:3072
	ds_read_b128 v[156:159], v174
	ds_read_b128 v[166:169], v174 offset:1024
	ds_read_b128 v[170:173], v174 offset:2048
	ds_read_b128 v[174:177], v174 offset:3072
	s_add_u32 s34, s34, 0x40000
	s_addc_u32 s35, s35, 0
	s_mov_b32 m0, s49
	ds_read_b128 v[178:181], v165 offset:32768
	ds_read_b128 v[182:185], v165 offset:33792
	ds_read_b128 v[186:189], v165 offset:34816
	ds_read_b128 v[190:193], v165 offset:35840
	ds_read_b128 v[194:197], v165 offset:36864
	ds_read_b128 v[198:201], v165 offset:37888
	ds_read_b128 v[202:205], v165 offset:38912
	ds_read_b128 v[224:227], v165 offset:39936
	global_load_lds_dwordx4 v150, s[34:35]
	v_lshl_add_u64 v[228:229], s[34:35], 0, v[146:147]
	s_mov_b32 m0, s57
	s_nop 0
	global_load_lds_dwordx4 v146, s[34:35]
	s_waitcnt vmcnt(8)
	s_waitcnt lgkmcnt(0)
	s_barrier
	s_setprio 1
	s_waitcnt lgkmcnt(0)
	v_mfma_f32_16x16x32_bf16 v[140:143], v[84:87], v[178:181], v[140:143]
	v_mfma_f32_16x16x32_bf16 v[136:139], v[96:99], v[178:181], v[136:139]
	v_mfma_f32_16x16x32_bf16 v[132:135], v[84:87], v[186:189], v[132:135]
	v_mfma_f32_16x16x32_bf16 v[128:131], v[96:99], v[186:189], v[128:131]
	v_mfma_f32_16x16x32_bf16 v[124:127], v[84:87], v[194:197], v[124:127]
	v_mfma_f32_16x16x32_bf16 v[120:123], v[96:99], v[194:197], v[120:123]
	v_mfma_f32_16x16x32_bf16 v[116:119], v[84:87], v[202:205], v[116:119]
	v_mfma_f32_16x16x32_bf16 v[112:115], v[96:99], v[202:205], v[112:115]
	v_mfma_f32_16x16x32_bf16 v[140:143], v[88:91], v[182:185], v[140:143]
	v_mfma_f32_16x16x32_bf16 v[136:139], v[100:103], v[182:185], v[136:139]
	v_mfma_f32_16x16x32_bf16 v[132:135], v[88:91], v[190:193], v[132:135]
	v_mfma_f32_16x16x32_bf16 v[128:131], v[100:103], v[190:193], v[128:131]
	v_mfma_f32_16x16x32_bf16 v[124:127], v[88:91], v[198:201], v[124:127]
	v_mfma_f32_16x16x32_bf16 v[120:123], v[100:103], v[198:201], v[120:123]
	v_mfma_f32_16x16x32_bf16 v[116:119], v[88:91], v[224:227], v[116:119]
	v_mfma_f32_16x16x32_bf16 v[112:115], v[100:103], v[224:227], v[112:115]
	s_setprio 0
	s_setprio 1
	v_mfma_f32_16x16x32_bf16 v[60:63], v[156:159], v[178:181], v[60:63]
	v_mfma_f32_16x16x32_bf16 v[56:59], v[170:173], v[178:181], v[56:59]
	v_mfma_f32_16x16x32_bf16 v[52:55], v[156:159], v[186:189], v[52:55]
	v_mfma_f32_16x16x32_bf16 v[48:51], v[170:173], v[186:189], v[48:51]
	v_mfma_f32_16x16x32_bf16 v[44:47], v[156:159], v[194:197], v[44:47]
	v_mfma_f32_16x16x32_bf16 v[40:43], v[170:173], v[194:197], v[40:43]
	v_mfma_f32_16x16x32_bf16 v[36:39], v[156:159], v[202:205], v[36:39]
	v_mfma_f32_16x16x32_bf16 v[32:35], v[170:173], v[202:205], v[32:35]
	v_mfma_f32_16x16x32_bf16 v[60:63], v[166:169], v[182:185], v[60:63]
	v_mfma_f32_16x16x32_bf16 v[56:59], v[174:177], v[182:185], v[56:59]
	v_mfma_f32_16x16x32_bf16 v[52:55], v[166:169], v[190:193], v[52:55]
	v_mfma_f32_16x16x32_bf16 v[48:51], v[174:177], v[190:193], v[48:51]
	v_mfma_f32_16x16x32_bf16 v[44:47], v[166:169], v[198:201], v[44:47]
	v_mfma_f32_16x16x32_bf16 v[40:43], v[174:177], v[198:201], v[40:43]
	v_mfma_f32_16x16x32_bf16 v[36:39], v[166:169], v[224:227], v[36:39]
	v_mfma_f32_16x16x32_bf16 v[32:35], v[174:177], v[224:227], v[32:35]
	s_setprio 0
	s_barrier
	s_add_i32 s28, s28, s36
	v_lshl_add_u64 v[160:161], v[160:161], 0, s[76:77]
	s_mov_b32 m0, s28
	ds_read_b128 v[178:181], v165 offset:49152
	ds_read_b128 v[182:185], v165 offset:50176
	ds_read_b128 v[186:189], v165 offset:51200
	ds_read_b128 v[190:193], v165 offset:52224
	ds_read_b128 v[194:197], v165 offset:53248
	ds_read_b128 v[198:201], v165 offset:54272
	ds_read_b128 v[202:205], v165 offset:55296
	ds_read_b128 v[224:227], v165 offset:56320
	global_load_lds_dwordx4 v[160:161], off
	s_add_i32 m0, s28, 0x2000
	s_add_u32 s4, s4, 0x40080
	v_lshl_add_u64 v[160:161], v[206:207], 0, s[76:77]
	s_addc_u32 s5, s5, 0
	s_add_i32 s28, s29, s36
	global_load_lds_dwordx4 v[160:161], off
	s_mov_b32 m0, s28
	s_nop 0
	global_load_lds_dwordx4 v148, s[4:5]
	s_add_i32 m0, s28, 0x2000
	s_nop 0
	global_load_lds_dwordx4 v144, s[4:5]
	v_lshl_add_u64 v[160:161], v[210:211], 0, s[76:77]
	s_mov_b32 m0, s7
	s_nop 0
	global_load_lds_dwordx4 v[160:161], off
	v_lshl_add_u64 v[160:161], v[212:213], 0, s[76:77]
	s_mov_b32 m0, s58
	s_nop 0
	global_load_lds_dwordx4 v[160:161], off
	s_waitcnt vmcnt(8)
	s_waitcnt lgkmcnt(0)
	s_barrier
	s_setprio 1
	s_waitcnt lgkmcnt(0)
	v_mfma_f32_16x16x32_bf16 v[108:111], v[84:87], v[178:181], v[108:111]
	v_mfma_f32_16x16x32_bf16 v[104:107], v[96:99], v[178:181], v[104:107]
	v_mfma_f32_16x16x32_bf16 v[92:95], v[84:87], v[186:189], v[92:95]
	v_mfma_f32_16x16x32_bf16 v[80:83], v[96:99], v[186:189], v[80:83]
	v_mfma_f32_16x16x32_bf16 v[76:79], v[84:87], v[194:197], v[76:79]
	v_mfma_f32_16x16x32_bf16 v[72:75], v[96:99], v[194:197], v[72:75]
	v_mfma_f32_16x16x32_bf16 v[68:71], v[84:87], v[202:205], v[68:71]
	v_mfma_f32_16x16x32_bf16 v[64:67], v[96:99], v[202:205], v[64:67]
	v_mfma_f32_16x16x32_bf16 v[108:111], v[88:91], v[182:185], v[108:111]
	v_mfma_f32_16x16x32_bf16 v[104:107], v[100:103], v[182:185], v[104:107]
	v_mfma_f32_16x16x32_bf16 v[92:95], v[88:91], v[190:193], v[92:95]
	v_mfma_f32_16x16x32_bf16 v[80:83], v[100:103], v[190:193], v[80:83]
	v_mfma_f32_16x16x32_bf16 v[76:79], v[88:91], v[198:201], v[76:79]
	v_mfma_f32_16x16x32_bf16 v[72:75], v[100:103], v[198:201], v[72:75]
	v_mfma_f32_16x16x32_bf16 v[68:71], v[88:91], v[224:227], v[68:71]
	v_mfma_f32_16x16x32_bf16 v[64:67], v[100:103], v[224:227], v[64:67]
	s_setprio 0
	s_setprio 1
	v_mfma_f32_16x16x32_bf16 v[28:31], v[156:159], v[178:181], v[28:31]
	v_mfma_f32_16x16x32_bf16 v[24:27], v[170:173], v[178:181], v[24:27]
	v_mfma_f32_16x16x32_bf16 v[20:23], v[156:159], v[186:189], v[20:23]
	v_mfma_f32_16x16x32_bf16 v[16:19], v[170:173], v[186:189], v[16:19]
	v_mfma_f32_16x16x32_bf16 v[12:15], v[156:159], v[194:197], v[12:15]
	v_mfma_f32_16x16x32_bf16 v[8:11], v[170:173], v[194:197], v[8:11]
	v_mfma_f32_16x16x32_bf16 v[4:7], v[156:159], v[202:205], v[4:7]
	v_mfma_f32_16x16x32_bf16 v[0:3], v[170:173], v[202:205], v[0:3]
	v_mfma_f32_16x16x32_bf16 v[28:31], v[166:169], v[182:185], v[28:31]
	v_mfma_f32_16x16x32_bf16 v[24:27], v[174:177], v[182:185], v[24:27]
	v_mfma_f32_16x16x32_bf16 v[20:23], v[166:169], v[190:193], v[20:23]
	v_mfma_f32_16x16x32_bf16 v[16:19], v[174:177], v[190:193], v[16:19]
	v_mfma_f32_16x16x32_bf16 v[12:15], v[166:169], v[198:201], v[12:15]
	v_mfma_f32_16x16x32_bf16 v[8:11], v[174:177], v[198:201], v[8:11]
	v_mfma_f32_16x16x32_bf16 v[4:7], v[166:169], v[224:227], v[4:7]
	v_mfma_f32_16x16x32_bf16 v[0:3], v[174:177], v[224:227], v[0:3]
	s_setprio 0
	s_barrier
	s_add_i32 s68, s68, 2
	s_add_u32 s10, s10, 0x100
	s_addc_u32 s11, s11, 0
	s_add_u32 s63, s63, 0x100
	s_addc_u32 s66, s66, 0
	s_cmp_gt_u32 s68, 13
	s_cbranch_scc0 .LBB0_388
	s_and_b64 vcc, exec, s[16:17]
	s_cbranch_vccz .LBB0_391
	s_barrier
